# scan loops (GLA, HGRN2, retention): static s_setprio 1 for waves 4-7 during the chunk loop
# speedup vs baseline: 1.0049x; 1.0041x over previous
; __device__ __forceinline__ char* WS(const Params& p) { return p.ws + opaque0(); }
; template <int MODE>
; __device__ void scan_unit(int swave, const Params& p, int j, int b, int h, int dir, char* shm) {
;     ...
;   const int tid = tidx, lane = tid & 63, w = tid >> 6, r = lane & 15, q4 = lane >> 4;
;   const int wk = w % KS, wv = w / KS, slab = wk * 64, vt0 = wv * NVT;
;   const int hh = MODE == 1 ? 4 + h : h;
;   bf16_t* O = (bf16_t*)(WS(p) + OFF_OFB + (dir ? (MODE == 2 ? OFB_OB_ODD : OFB_OB_EVEN) : 0)) + hh * DV;
;   const size_t rowbase = (size_t)b * SEQ;
;   const int ti = lane & 15, dp = (tid >> 4) * 2;
;   float wa2r[32]; float bav0 = 0.f, bav1 = 0.f, lbv0 = 0.f, lbv1 = 0.f, lg = 0.f;
;   const float2* rope = (const float2*)(WS(p) + OFF_MISC + MISC_ROPE);
;   if (MODE == 0) {
;     const float* wa2 = INP(p, 6) + ((size_t)(j * 2 + dir) * 16) * 256 + h * 64 + dp;
; #pragma unroll
;     for (int rr = 0; rr < 16; ++rr) { const float2 t2 = *(const float2*)(wa2 + rr * 256); wa2r[2 * rr] = t2.x; wa2r[2 * rr + 1] = t2.y; }
;     const float2 bb = *(const float2*)(INP(p, 7) + (j * 2 + dir) * 256 + h * 64 + dp);
;     bav0 = bb.x; bav1 = bb.y;
;   } else if (MODE == 1) {
;     if (j > 0) {
;       const float2 l0 = *(const float2*)(INP(p, 9) + (dir * 2 + 0) * 256 + h * 64 + dp), l1 = *(const float2*)(INP(p, 9) + (dir * 2 + 1) * 256 + h * 64 + dp);
;       lbv0 = 1.f / (1.f + __expf(l0.x - l1.x)); lbv1 = 1.f / (1.f + __expf(l0.y - l1.y));
;     }
;   } else {
;     lg = log1pf(-exp2f((dir ? -5.5f : -5.0f) - (float)h));
;   }
;   const int vg = tid >> 4;
;   const float ret_ein = __expf(lg * (float)(ti + 1)), ret_eti = __expf(-lg * (float)(ti + 1)), ret_eout = __expf(lg * (float)(15 - ti)), ret_dd = __expf(lg * 16.f);
;   struct Raw { unsigned q, k, q2, k2; uint4 lr0, lr1; uint2 v; unsigned v30, v31, v32; float4 cs; };
;   auto tokof = [&](int c, int i) { int t = c * 16 + i; return dir ? (SEQ - 1 - t) : t; };
;   auto load_raw = [&](int c, Raw& R) {
;     const int tok = tokof(c, ti);
;     const bf16_t* row = P + (rowbase + tok) * LDP;
;     if (MODE == 0) {
;       R.q = *(const unsigned*)(row + E_GQ + h * 64 + dp); R.k = *(const unsigned*)(row + E_GK + h * 64 + dp);
;       const uint4* lrp = (const uint4*)(row + (dir ? E_GLB : E_GLF));
;       R.lr0 = lrp[0]; R.lr1 = lrp[1];
;       R.v = *(const uint2*)(row + E_GV + h * 128 + vg * 4);
;     } else if (MODE == 1) {
.LBB0_562:
	s_and_b64 vcc, exec, s[0:1]
	s_cbranch_vccz .LBB0_627
	v_readlane_b32 s0, v246, 4
	v_readlane_b32 s12, v248, 8
	s_ashr_i32 s4, s0, 3
	s_bfe_u32 s8, s0, 0x20001
	s_and_b32 s5, s0, 1
	v_mov_b32_e32 v111, v147
	s_mov_b64 s[0:1], 0
	v_readlane_b32 s14, v248, 10
	v_readlane_b32 s15, v248, 11
	s_add_u32 s7, s14, s0
	s_addc_u32 s9, s15, s1
	s_cmp_eq_u32 s5, 0
	s_mov_b64 s[2:3], 0
	s_cselect_b64 s[0:1], -1, 0
	s_mov_b64 s[10:11], 0
	s_ashr_i32 s5, s4, 31
	v_cndmask_b32_e64 v0, v150, v151, s[0:1]
	v_cvt_f32_ubyte0_e32 v1, s8
	s_add_u32 s12, s14, s10
	v_sub_f32_e32 v0, v0, v1
	s_mov_b32 s10, 0xc2fc0000
	v_cmp_gt_f32_e32 vcc, s10, v0
	v_readlane_b32 s13, v248, 9
	s_addc_u32 s13, s15, s11
	v_cndmask_b32_e32 v1, 0, v152, vcc
	v_add_f32_e32 v0, v0, v1
	v_exp_f32_e32 v0, v0
	s_and_b64 s[10:11], vcc, exec
	s_cselect_b32 s10, 0xffffffc0, 0
	v_ashrrev_i32_e32 v2, 3, v111
	v_ldexp_f32 v36, v0, s10
	s_waitcnt vmcnt(0)
	v_sub_f32_e32 v4, 1.0, v36
	v_add_f32_e32 v0, -1.0, v4
	v_sub_f32_e32 v1, v0, v4
	v_add_f32_e32 v1, 1.0, v1
	v_sub_f32_e64 v0, -v36, v0
	v_add_f32_e32 v5, v0, v1
	v_frexp_mant_f32_e32 v6, v4
	v_cvt_f64_f32_e32 v[0:1], v4
	s_mov_b32 s10, 0x3f2aaaab
	v_frexp_exp_i32_f64_e32 v0, v[0:1]
	v_cmp_gt_f32_e32 vcc, s10, v6
	s_mov_b32 s10, 0x3f317218
	s_add_u32 s44, s7, 0xc000000
	s_waitcnt vmcnt(0)
	v_subbrev_co_u32_e32 v10, vcc, 0, v0, vcc
	v_sub_u32_e32 v0, 0, v10
	v_ldexp_f32 v1, v4, v0
	v_add_f32_e32 v4, -1.0, v1
	v_add_f32_e32 v6, 1.0, v1
	v_ldexp_f32 v0, v5, v0
	v_add_f32_e32 v5, 1.0, v4
	v_add_f32_e32 v7, -1.0, v6
	v_sub_f32_e32 v5, v1, v5
	v_sub_f32_e32 v1, v1, v7
	v_add_f32_e32 v5, v0, v5
	v_add_f32_e32 v0, v0, v1
	v_add_f32_e32 v11, v6, v0
	v_rcp_f32_e32 v13, v11
	v_sub_f32_e32 v1, v11, v6
	v_sub_f32_e32 v12, v0, v1
	v_add_f32_e32 v1, v4, v5
	v_mul_f32_e32 v15, v1, v13
	v_sub_f32_e32 v0, v1, v4
	v_mul_f32_e32 v4, v11, v15
	v_fma_f32 v6, v15, v11, -v4
	v_fmac_f32_e32 v6, v15, v12
	v_sub_f32_e32 v14, v5, v0
	v_add_f32_e32 v0, v4, v6
	v_sub_f32_e32 v5, v1, v0
	v_pk_add_f32 v[8:9], v[0:1], v[4:5] neg_lo:[0,1] neg_hi:[0,1]
	v_mov_b32_e32 v7, v0
	v_pk_add_f32 v[0:1], v[8:9], v[6:7] neg_lo:[0,1] neg_hi:[0,1]
	s_movk_i32 s7, 0x7ff
	v_add_f32_e32 v1, v14, v1
	v_add_f32_e32 v0, v0, v1
	v_add_f32_e32 v1, v5, v0
	v_mul_f32_e32 v14, v13, v1
	v_mul_f32_e32 v4, v11, v14
	v_fma_f32 v6, v14, v11, -v4
	v_fmac_f32_e32 v6, v14, v12
	v_sub_f32_e32 v5, v5, v1
	v_add_f32_e32 v11, v0, v5
	v_add_f32_e32 v0, v4, v6
	v_sub_f32_e32 v5, v1, v0
	v_pk_add_f32 v[8:9], v[0:1], v[4:5] neg_lo:[0,1] neg_hi:[0,1]
	v_mov_b32_e32 v7, v0
	v_pk_add_f32 v[0:1], v[8:9], v[6:7] neg_lo:[0,1] neg_hi:[0,1]
	v_and_b32_e32 v116, 15, v111
	v_add_f32_e32 v1, v11, v1
	v_add_f32_e32 v0, v0, v1
	v_add_f32_e32 v1, v15, v14
	v_add_f32_e32 v0, v5, v0
	v_sub_f32_e32 v4, v1, v15
	v_mul_f32_e32 v0, v13, v0
	v_sub_f32_e32 v4, v14, v4
	v_add_f32_e32 v4, v4, v0
	v_add_f32_e32 v6, v1, v4
	v_mul_f32_e32 v7, v6, v6
	v_fmamk_f32 v0, v7, 0x3e9b6dac, v148
	v_fmaak_f32 v135, v7, v0, 0x3f2aaada
	v_cvt_f32_i32_e32 v0, v10
	v_sub_f32_e32 v1, v6, v1
	v_sub_f32_e32 v1, v4, v1
	v_ldexp_f32 v8, v1, 1
	v_mul_f32_e32 v1, v6, v7
	v_ldexp_f32 v5, v6, 1
	v_pk_mul_f32 v[6:7], v[0:1], v[134:135]
	v_and_b32_e32 v12, -2, v2
	v_fma_f32 v4, v0, s10, -v6
	v_fmac_f32_e32 v4, 0xb102e308, v0
	v_pk_add_f32 v[0:1], v[6:7], v[4:5]
	v_bitop3_b32 v2, v111, s7, 15 bitop3:0x6c
	v_sub_f32_e32 v5, v1, v5
	v_sub_f32_e32 v5, v7, v5
	s_addc_u32 s45, s9, 0
	s_lshl_b64 s[18:19], s[4:5], 11
	v_cndmask_b32_e64 v2, v2, v116, s[0:1]
	v_add_f32_e32 v17, v8, v5
	v_or_b32_e32 v5, s18, v2
	v_mov_b64_e32 v[18:19], s[44:45]
	s_add_u32 s4, s12, 0x1eb9c000
	v_mad_u64_u32 v[8:9], s[10:11], v5, s55, v[18:19]
	s_addc_u32 s5, s13, 0
	v_ashrrev_i32_e32 v11, 4, v111
	v_mad_i32_i24 v9, s19, v155, v9
	s_lshl_b32 s94, s8, 8
	v_ashrrev_i32_e32 v13, 31, v12
	s_mul_i32 s6, s8, 0xc0
	v_lshl_add_u64 v[14:15], v[8:9], 0, s[94:95]
	v_lshlrev_b64 v[118:119], 1, v[12:13]
	v_mul_lo_u32 v22, v11, 6
	v_lshl_add_u64 v[14:15], v[14:15], 0, v[118:119]
	v_lshlrev_b32_e32 v2, 9, v2
	s_lshl_b32 s46, s6, 1
	s_mov_b32 s47, s95
	v_ashrrev_i32_e32 v23, 31, v22
	s_barrier
	global_load_dword v37, v[14:15], off
	global_load_dword v38, v[14:15], off offset:128
	global_load_dword v39, v[14:15], off offset:1024
	global_load_dword v40, v[14:15], off offset:1152
	v_lshl_add_u64 v[20:21], s[4:5], 0, v[2:3]
	v_lshlrev_b64 v[14:15], 3, v[12:13]
	v_lshl_add_u64 v[8:9], v[8:9], 0, s[46:47]
	v_lshlrev_b64 v[122:123], 1, v[22:23]
	v_mov_b32_e32 v16, v6
	v_lshl_add_u64 v[20:21], v[20:21], 0, v[14:15]
	v_lshl_add_u64 v[8:9], v[8:9], 0, v[122:123]
	v_pk_add_f32 v[6:7], v[0:1], v[6:7] neg_lo:[0,1] neg_hi:[0,1]
	global_load_dwordx3 v[8:10], v[8:9], off offset:2048
	s_nop 0
	global_load_dwordx4 v[26:29], v[20:21], off
	v_pk_add_f32 v[20:21], v[0:1], v[16:17]
	v_mov_b32_e32 v5, v0
	v_mov_b32_e32 v7, v21
	v_pk_add_f32 v[30:31], v[4:5], v[6:7] neg_lo:[0,1] neg_hi:[0,1]
	v_pk_add_f32 v[4:5], v[4:5], v[6:7]
	v_mov_b32_e32 v24, v1
	v_pk_add_f32 v[6:7], v[4:5], v[0:1] op_sel:[1,0] op_sel_hi:[0,1] neg_lo:[0,1] neg_hi:[0,1]
	v_pk_add_f32 v[22:23], v[20:21], v[6:7] op_sel_hi:[1,0] neg_lo:[0,1] neg_hi:[0,1]
	v_mov_b32_e32 v20, v21
	v_mov_b32_e32 v21, v5
	v_mov_b32_e32 v25, v6
	v_pk_add_f32 v[6:7], v[20:21], v[24:25] neg_lo:[0,1] neg_hi:[0,1]
	v_mov_b32_e32 v16, v17
	v_mov_b32_e32 v17, v0
	v_pk_add_f32 v[0:1], v[16:17], v[6:7] neg_lo:[0,1] neg_hi:[0,1]
	v_mov_b32_e32 v22, v30
	v_pk_add_f32 v[16:17], v[22:23], v[0:1]
	v_mov_b32_e32 v31, v5
	v_pk_add_f32 v[6:7], v[16:17], v[16:17] op_sel:[0,1] op_sel_hi:[1,0]
	s_movk_i32 s6, 0x7ef
	v_pk_add_f32 v[20:21], v[4:5], v[6:7] op_sel:[1,0] op_sel_hi:[0,1]
; template <int MODE>
; __device__ void scan_unit(int swave, const Params& p, int j, int b, int h, int dir, char* shm) {
;     ...
;   const float ret_ein = __expf(lg * (float)(ti + 1)), ret_eti = __expf(-lg * (float)(ti + 1)), ret_eout = __expf(lg * (float)(15 - ti)), ret_dd = __expf(lg * 16.f);
;   struct Raw { unsigned q, k, q2, k2; uint4 lr0, lr1; uint2 v; unsigned v30, v31, v32; float4 cs; };
;   auto tokof = [&](int c, int i) { int t = c * 16 + i; return dir ? (SEQ - 1 - t) : t; };
;   auto load_raw = [&](int c, Raw& R) {
;     const int tok = tokof(c, ti);
;     const bf16_t* row = P + (rowbase + tok) * LDP;
;     if (MODE == 0) {
;       R.q = *(const unsigned*)(row + E_GQ + h * 64 + dp); R.k = *(const unsigned*)(row + E_GK + h * 64 + dp);
;       const uint4* lrp = (const uint4*)(row + (dir ? E_GLB : E_GLF));
;       R.lr0 = lrp[0]; R.lr1 = lrp[1];
;       R.v = *(const uint2*)(row + E_GV + h * 128 + vg * 4);
;     } else if (MODE == 1) {
;       R.q = *(const unsigned*)(row + E_HQ + h * 64 + dp); R.k = *(const unsigned*)(row + (dir ? E_HZB : E_HZF) + h * 64 + dp);
;       R.v = *(const uint2*)(row + E_HI + h * 128 + vg * 4);
;     } else {
;       R.q = *(const unsigned*)(row + O_RQ + h * 128 + dp); R.q2 = *(const unsigned*)(row + O_RQ + h * 128 + 64 + dp);
;       R.k = *(const unsigned*)(row + O_RK + h * 128 + dp); R.k2 = *(const unsigned*)(row + O_RK + h * 128 + 64 + dp);
;       R.cs = *(const float4*)(rope + tok * 64 + dp);
;       const unsigned* vp = (const unsigned*)(row + O_RV + h * 192 + vg * 6);
;       R.v30 = vp[0]; R.v31 = vp[1]; R.v32 = vp[2];
;     ...
;       const float KSC = 0.08838834764831845f;
;       const float qx0 = lo_bf(R.q), qx1 = hi_bf(R.q), qy0 = lo_bf(R.q2), qy1 = hi_bf(R.q2);
;       const float kx0 = lo_bf(R.k) * KSC, kx1 = hi_bf(R.k) * KSC, ky0 = lo_bf(R.k2) * KSC, ky1 = hi_bf(R.k2) * KSC;
;       const float c0 = R.cs.x, sn0 = R.cs.y, c1 = R.cs.z, sn1 = R.cs.w;
;       const float qa0 = qx0 * c0 - qy0 * sn0, qb0 = qx0 * sn0 + qy0 * c0, qa1 = qx1 * c1 - qy1 * sn1, qb1 = qx1 * sn1 + qy1 * c1;
;       const float ka0 = kx0 * c0 - ky0 * sn0, kb0 = kx0 * sn0 + ky0 * c0, ka1 = kx1 * c1 - ky1 * sn1, kb1 = kx1 * sn1 + ky1 * c1;
;       const float ein = ret_ein, eti = ret_eti, eout = ret_eout;
;       *(unsigned*)(qin + ti * QS + dp) = pk2(qa0 * ein, qa1 * ein); *(unsigned*)(qin + ti * QS + 64 + dp) = pk2(qb0 * ein, qb1 * ein);
	v_mov_b32_e32 v17, v20
	v_pk_add_f32 v[32:33], v[16:17], v[30:31] neg_lo:[0,1] neg_hi:[0,1]
	v_mov_b32_e32 v1, v6
	v_pk_add_f32 v[34:35], v[0:1], v[32:33] neg_lo:[0,1] neg_hi:[0,1]
	v_or_b32_e32 v13, 16, v116
	v_bitop3_b32 v0, v111, s6, 15 bitop3:0x6c
	v_cndmask_b32_e64 v2, v0, v13, s[0:1]
	v_or_b32_e32 v0, s18, v2
	v_mad_u64_u32 v[0:1], s[6:7], v0, s55, v[18:19]
	v_mad_i32_i24 v1, s19, v155, v1
	v_lshl_add_u64 v[4:5], v[0:1], 0, s[94:95]
	v_lshl_add_u64 v[4:5], v[4:5], 0, v[118:119]
	v_lshlrev_b32_e32 v2, 9, v2
	global_load_dword v24, v[4:5], off
	global_load_dword v23, v[4:5], off offset:128
	global_load_dword v22, v[4:5], off offset:1024
	global_load_dword v21, v[4:5], off offset:1152
	v_lshl_add_u64 v[4:5], s[4:5], 0, v[2:3]
	v_lshl_add_u64 v[0:1], v[0:1], 0, s[46:47]
	v_lshl_add_u64 v[4:5], v[4:5], 0, v[14:15]
	v_lshl_add_u64 v[0:1], v[0:1], 0, v[122:123]
	global_load_dwordx4 v[4:7], v[4:5], off
	s_nop 0
	global_load_dwordx3 v[0:2], v[0:1], off offset:2048
	v_sub_f32_e32 v16, v16, v32
	v_sub_f32_e32 v16, v30, v16
	v_add_f32_e32 v16, v34, v16
	v_add_f32_e32 v16, v16, v35
	v_add_f32_e32 v16, v20, v16
	v_cmp_nlt_f32_e32 vcc, 1.0, v36
	s_mov_b32 s6, 0x33800000
	v_add_u32_e32 v17, 1, v116
	v_cndmask_b32_e32 v16, v153, v16, vcc
	v_cmp_neq_f32_e32 vcc, 1.0, v36
	v_cvt_f32_ubyte0_e32 v17, v17
	v_bitop3_b32 v19, v111, 15, v111 bitop3:0xc
	v_cndmask_b32_e32 v16, v154, v16, vcc
	v_cmp_gt_f32_e32 vcc, s6, v36
	v_cvt_f32_ubyte0_e32 v19, v19
	s_mov_b32 s6, 0x3db504f3
	v_cndmask_b32_e64 v16, v16, -v36, vcc
	v_mul_f32_e32 v18, v16, v17
	v_mul_f32_e32 v18, 0x3fb8aa3b, v18
	v_mul_f32_e64 v17, -v16, v17
	v_mul_f32_e32 v19, v16, v19
	v_mul_f32_e32 v16, 0x41800000, v16
	v_mul_f32_e32 v17, 0x3fb8aa3b, v17
	v_mul_f32_e32 v16, 0x3fb8aa3b, v16
	v_exp_f32_e32 v124, v18
	v_mul_f32_e32 v19, 0x3fb8aa3b, v19
	v_exp_f32_e32 v126, v17
	v_exp_f32_e32 v128, v16
	s_waitcnt vmcnt(0)
	v_lshlrev_b32_e32 v16, 16, v37
	v_and_b32_e32 v17, 0xffff0000, v37
	s_waitcnt vmcnt(10)
	v_lshlrev_b32_e32 v30, 16, v38
	v_and_b32_e32 v31, 0xffff0000, v38
	v_exp_f32_e32 v117, v19
	s_waitcnt vmcnt(8)
	v_lshlrev_b32_e32 v34, 16, v40
	v_and_b32_e32 v35, 0xffff0000, v40
	v_lshlrev_b32_e32 v32, 16, v39
	v_and_b32_e32 v33, 0xffff0000, v39
	v_cmp_ne_u32_e32 vcc, 0, v116
	s_waitcnt vmcnt(6)
	v_mov_b32_e32 v37, v28
	v_mov_b32_e32 v28, v27
	v_mov_b32_e32 v36, v26
	v_pk_mul_f32 v[18:19], v[28:29], v[30:31]
	v_pk_mul_f32 v[26:27], v[34:35], s[6:7] op_sel_hi:[1,0]
	v_pk_fma_f32 v[18:19], v[36:37], v[16:17], v[18:19] neg_lo:[0,0,1] neg_hi:[0,0,1]
	v_pk_mul_f32 v[16:17], v[28:29], v[16:17]
	v_pk_mul_f32 v[18:19], v[124:125], v[18:19] op_sel_hi:[0,1]
	v_cvt_pk_bf16_f32 v20, v18, v19
	v_mul_u32_u24_e32 v19, 0x88, v116
	v_pk_fma_f32 v[16:17], v[36:37], v[30:31], v[16:17]
	v_lshl_add_u32 v18, v19, 1, 0
	v_pk_mul_f32 v[16:17], v[124:125], v[16:17] op_sel_hi:[0,1]
	v_lshl_add_u32 v121, v12, 1, v18
	v_cvt_pk_bf16_f32 v16, v16, v17
	ds_write2_b32 v121, v20, v16 offset1:32
	v_pk_mul_f32 v[16:17], v[32:33], s[6:7] op_sel_hi:[1,0]
	v_pk_mul_f32 v[30:31], v[28:29], v[26:27]
	v_add_u32_e32 v135, 0x1000, v121
	v_pk_fma_f32 v[30:31], v[36:37], v[16:17], v[30:31] neg_lo:[0,0,1] neg_hi:[0,0,1]
	v_pk_mul_f32 v[16:17], v[16:17], v[28:29]
	v_pk_mul_f32 v[32:33], v[126:127], v[30:31] op_sel_hi:[0,1]
	v_pk_fma_f32 v[16:17], v[26:27], v[36:37], v[16:17]
	v_cvt_pk_bf16_f32 v20, v32, v33
	v_pk_mul_f32 v[26:27], v[126:127], v[16:17] op_sel_hi:[0,1]
	v_cvt_pk_bf16_f32 v25, v26, v27
	ds_write2_b32 v135, v20, v25 offset0:64 offset1:96
	v_mul_f32_e32 v20, v117, v30
	v_cvt_pk_bf16_f32 v25, v20, s0
	v_lshl_or_b32 v20, v12, 4, v116
	v_lshl_add_u32 v136, v20, 1, 0
	v_mul_f32_e32 v16, v117, v16
	ds_write_b16 v136, v25 offset:8704
	v_mul_f32_e32 v25, v117, v31
	v_cvt_pk_bf16_f32 v16, v16, s0
	v_cvt_pk_bf16_f32 v25, v25, s0
	ds_write_b16 v136, v16 offset:10752
	v_mul_f32_e32 v16, v117, v17
	ds_write_b16 v136, v25 offset:8736
	v_cvt_pk_bf16_f32 v16, v16, s0
	v_cmp_eq_u32_e64 s[16:17], 0, v116
	v_lshl_add_u32 v25, v12, 2, 0
	ds_write_b16 v136, v16 offset:10784
	s_and_saveexec_b64 s[6:7], s[16:17]
	v_mov_b32_e32 v129, v128
	v_add_u32_e32 v16, 0x5000, v25
	ds_write2_b64 v16, v[128:129], v[128:129] offset1:32
	s_or_b64 exec, exec, s[6:7]
	s_movk_i32 s6, 0x78
	v_mad_u64_u32 v[16:17], s[6:7], v11, s6, v[116:117]
	v_lshl_add_u32 v137, v16, 1, 0
	ds_write_b16 v137, v8 offset:12800
	ds_write_b16_d16_hi v137, v8 offset:12840
	ds_write_b16 v137, v9 offset:12880
	ds_write_b16_d16_hi v137, v9 offset:12920
	ds_write_b16 v137, v10 offset:12960
	ds_write_b16_d16_hi v137, v10 offset:13000
	s_waitcnt vmcnt(0)
	v_lshlrev_b32_e32 v10, 16, v23
	v_and_b32_e32 v11, 0xffff0000, v23
	s_waitcnt vmcnt(1)
; template <int MODE>
; __device__ void scan_unit(int swave, const Params& p, int j, int b, int h, int dir, char* shm) {
;     ...
;   auto load_raw = [&](int c, Raw& R) {
;     const int tok = tokof(c, ti);
;     const bf16_t* row = P + (rowbase + tok) * LDP;
;     if (MODE == 0) {
;       R.q = *(const unsigned*)(row + E_GQ + h * 64 + dp); R.k = *(const unsigned*)(row + E_GK + h * 64 + dp);
;       const uint4* lrp = (const uint4*)(row + (dir ? E_GLB : E_GLF));
;       R.lr0 = lrp[0]; R.lr1 = lrp[1];
;       R.v = *(const uint2*)(row + E_GV + h * 128 + vg * 4);
;     } else if (MODE == 1) {
;       R.q = *(const unsigned*)(row + E_HQ + h * 64 + dp); R.k = *(const unsigned*)(row + (dir ? E_HZB : E_HZF) + h * 64 + dp);
;     ...
;       const float KSC = 0.08838834764831845f;
;       const float qx0 = lo_bf(R.q), qx1 = hi_bf(R.q), qy0 = lo_bf(R.q2), qy1 = hi_bf(R.q2);
;       const float kx0 = lo_bf(R.k) * KSC, kx1 = hi_bf(R.k) * KSC, ky0 = lo_bf(R.k2) * KSC, ky1 = hi_bf(R.k2) * KSC;
;       const float c0 = R.cs.x, sn0 = R.cs.y, c1 = R.cs.z, sn1 = R.cs.w;
;       const float qa0 = qx0 * c0 - qy0 * sn0, qb0 = qx0 * sn0 + qy0 * c0, qa1 = qx1 * c1 - qy1 * sn1, qb1 = qx1 * sn1 + qy1 * c1;
;       const float ka0 = kx0 * c0 - ky0 * sn0, kb0 = kx0 * sn0 + ky0 * c0, ka1 = kx1 * c1 - ky1 * sn1, kb1 = kx1 * sn1 + ky1 * c1;
;       const float ein = ret_ein, eti = ret_eti, eout = ret_eout;
;       *(unsigned*)(qin + ti * QS + dp) = pk2(qa0 * ein, qa1 * ein); *(unsigned*)(qin + ti * QS + 64 + dp) = pk2(qb0 * ein, qb1 * ein);
;       *(unsigned*)(ktil + ti * QS + dp) = pk2(ka0 * eti, ka1 * eti); *(unsigned*)(ktil + ti * QS + 64 + dp) = pk2(kb0 * eti, kb1 * eti);
;       koutT[dp * 16 + ti] = f2bf(ka0 * eout); koutT[(dp + 1) * 16 + ti] = f2bf(ka1 * eout);
;       koutT[(64 + dp) * 16 + ti] = f2bf(kb0 * eout); koutT[(65 + dp) * 16 + ti] = f2bf(kb1 * eout);
;       if (ti == 0) { const float dd = ret_dd; *(float2*)(dec + dp) = make_float2(dd, dd); *(float2*)(dec + 64 + dp) = make_float2(dd, dd); }
;       const int c6 = vg * 6;
;       vT[(c6 + 0) * VS + ti] = (bf16_t)(R.v30 & 0xffff); vT[(c6 + 1) * VS + ti] = (bf16_t)(R.v30 >> 16);
;       vT[(c6 + 2) * VS + ti] = (bf16_t)(R.v31 & 0xffff); vT[(c6 + 3) * VS + ti] = (bf16_t)(R.v31 >> 16);
;       vT[(c6 + 4) * VS + ti] = (bf16_t)(R.v32 & 0xffff); vT[(c6 + 5) * VS + ti] = (bf16_t)(R.v32 >> 16);
	v_mov_b32_e32 v29, v6
	v_mov_b32_e32 v6, v5
	v_lshlrev_b32_e32 v8, 16, v24
	v_and_b32_e32 v9, 0xffff0000, v24
	v_mov_b32_e32 v28, v4
	v_pk_mul_f32 v[4:5], v[6:7], v[10:11]
	v_mov_b32_e32 v125, v124
	v_pk_fma_f32 v[4:5], v[28:29], v[8:9], v[4:5] neg_lo:[0,0,1] neg_hi:[0,0,1]
	v_lshlrev_b32_e32 v26, 16, v22
	v_pk_mul_f32 v[4:5], v[124:125], v[4:5]
	v_and_b32_e32 v27, 0xffff0000, v22
	v_cvt_pk_bf16_f32 v17, v4, v5
	v_pk_mul_f32 v[4:5], v[6:7], v[8:9]
	v_lshlrev_b32_e32 v22, 16, v21
	v_pk_fma_f32 v[4:5], v[28:29], v[10:11], v[4:5]
	v_and_b32_e32 v23, 0xffff0000, v21
	v_pk_mul_f32 v[4:5], v[124:125], v[4:5]
	s_mov_b32 s6, 0x3db504f3
	v_cvt_pk_bf16_f32 v4, v4, v5
	v_add_u32_e32 v139, 0x5000, v121
	v_pk_mul_f32 v[8:9], v[22:23], s[6:7] op_sel_hi:[1,0]
	ds_write2_b32 v139, v17, v4 offset0:128 offset1:160
	v_pk_mul_f32 v[4:5], v[26:27], s[6:7] op_sel_hi:[1,0]
	v_pk_mul_f32 v[10:11], v[6:7], v[8:9]
	v_mov_b32_e32 v127, v126
	v_pk_fma_f32 v[10:11], v[28:29], v[4:5], v[10:11] neg_lo:[0,0,1] neg_hi:[0,0,1]
	v_pk_mul_f32 v[4:5], v[4:5], v[6:7]
	v_pk_mul_f32 v[22:23], v[126:127], v[10:11]
	v_pk_fma_f32 v[4:5], v[8:9], v[28:29], v[4:5]
	v_cvt_pk_bf16_f32 v17, v22, v23
	v_pk_mul_f32 v[6:7], v[126:127], v[4:5]
	v_add_u32_e32 v140, 0x6000, v121
	v_cvt_pk_bf16_f32 v6, v6, v7
	ds_write2_b32 v140, v17, v6 offset0:192 offset1:224
	v_mul_f32_e32 v6, v117, v10
	v_mul_f32_e32 v4, v117, v4
	v_cvt_pk_bf16_f32 v6, v6, s0
	v_cvt_pk_bf16_f32 v4, v4, s0
	ds_write_b16 v136, v6 offset:29696
	v_mul_f32_e32 v6, v117, v11
	ds_write_b16 v136, v4 offset:31744
	v_mul_f32_e32 v4, v117, v5
	v_cvt_pk_bf16_f32 v6, v6, s0
	v_cvt_pk_bf16_f32 v4, v4, s0
	ds_write_b16 v136, v6 offset:29728
	ds_write_b16 v136, v4 offset:31776
	s_and_saveexec_b64 s[6:7], vcc
	s_xor_b64 s[6:7], exec, s[6:7]
	s_mov_b32 s39, 0x2aaaaaab
	s_movk_i32 s40, 0xff40
	s_movk_i32 s41, 0xff
	s_or_saveexec_b64 s[6:7], s[6:7]
	s_lshl_b32 s8, s8, 7
	s_xor_b64 exec, exec, s[6:7]
	v_mov_b32_e32 v129, v128
	v_add_u32_e32 v4, 0xa000, v25
	ds_write2_b64 v4, v[128:129], v[128:129] offset0:64 offset1:96
	s_or_b64 exec, exec, s[6:7]
	v_readlane_b32 s12, v248, 8
	v_readlane_b32 s14, v248, 10
	v_readlane_b32 s15, v248, 11
	s_add_u32 s6, s14, s2
	s_addc_u32 s7, s15, s3
	s_and_b64 s[2:3], s[0:1], exec
	s_cselect_b32 s2, 0, 0x3000000
	s_add_u32 s2, s6, s2
	v_ashrrev_i32_e32 v4, 6, v111
	v_lshrrev_b32_e32 v5, 31, v111
	s_addc_u32 s3, s7, 0
	v_add_u32_e32 v5, v4, v5
	s_add_u32 s2, s2, s46
	s_waitcnt vmcnt(0)
	ds_write_b16 v137, v0 offset:33792
	ds_write_b16_d16_hi v137, v0 offset:33832
	ds_write_b16 v137, v1 offset:33872
	ds_write_b16_d16_hi v137, v1 offset:33912
	ds_write_b16 v137, v2 offset:33952
	ds_write_b16_d16_hi v137, v2 offset:33992
	v_or_b32_e32 v23, 32, v116
	v_xor_b32_e32 v0, 0x7df, v116
	v_lshrrev_b32_e32 v21, 1, v5
	v_and_b32_e32 v5, -2, v5
	s_addc_u32 s3, s3, 0
	v_cndmask_b32_e64 v2, v0, v23, s[0:1]
	v_sub_u32_e32 v22, v4, v5
	s_add_u32 s42, s2, 0x4000000
	v_or_b32_e32 v4, s18, v2
	v_mov_b64_e32 v[0:1], s[44:45]
	s_addc_u32 s43, s3, 0
	v_mad_u64_u32 v[4:5], s[2:3], v4, s55, v[0:1]
	v_mad_i32_i24 v5, s19, v155, v5
	s_lshl_b32 s94, s8, 1
	v_lshl_add_u64 v[6:7], v[4:5], 0, s[94:95]
	s_mov_b32 s48, s46
	s_mov_b32 s49, s95
	v_lshl_add_u64 v[6:7], v[6:7], 0, v[118:119]
	v_lshlrev_b32_e32 v2, 9, v2
	global_load_dword v242, v[6:7], off
	global_load_dword v241, v[6:7], off offset:128
	global_load_dword v240, v[6:7], off offset:1024
	global_load_dword v239, v[6:7], off offset:1152
	v_lshl_add_u64 v[6:7], s[4:5], 0, v[2:3]
	v_lshl_add_u64 v[4:5], v[4:5], 0, s[48:49]
	v_lshl_add_u64 v[6:7], v[6:7], 0, v[14:15]
	v_lshl_add_u64 v[4:5], v[4:5], 0, v[122:123]
	global_load_dwordx4 v[8:11], v[6:7], off
	global_load_dwordx3 v[112:114], v[4:5], off offset:2048
	v_or_b32_e32 v2, 48, v116
	v_xor_b32_e32 v4, 0x7cf, v116
	v_cndmask_b32_e64 v2, v4, v2, s[0:1]
	v_or_b32_e32 v4, s18, v2
	v_mad_u64_u32 v[0:1], s[2:3], v4, s55, v[0:1]
	v_mad_i32_i24 v1, s19, v155, v1
	v_lshl_add_u64 v[4:5], v[0:1], 0, s[94:95]
	v_lshl_add_u64 v[4:5], v[4:5], 0, v[118:119]
	v_lshlrev_b32_e32 v2, 9, v2
	global_load_dword v238, v[4:5], off
	global_load_dword v237, v[4:5], off offset:128
	global_load_dword v236, v[4:5], off offset:1024
	global_load_dword v235, v[4:5], off offset:1152
	v_lshl_add_u64 v[4:5], s[4:5], 0, v[2:3]
	v_lshl_add_u64 v[4:5], v[4:5], 0, v[14:15]
	v_lshl_add_u64 v[0:1], v[0:1], 0, s[48:49]
	v_lshl_add_u64 v[0:1], v[0:1], 0, v[122:123]
	global_load_dwordx4 v[4:7], v[4:5], off
	s_nop 0
	global_load_dwordx3 v[108:110], v[0:1], off offset:2048
	v_lshlrev_b32_e32 v1, 1, v19
	v_readlane_b32 s2, v247, 30
	v_bfe_u32 v17, v111, 4, 2
	v_lshlrev_b32_e32 v0, 2, v12
	v_add_u32_e32 v2, s2, v1
	v_readlane_b32 s2, v247, 32
	v_readlane_b32 s20, v247, 33
	v_add_u32_e32 v141, 0, v0
	v_add_u32_e32 v144, s2, v0
	v_add_u32_e32 v145, s20, v0
	v_lshlrev_b32_e32 v0, 2, v17
	v_readlane_b32 s13, v248, 9
	v_lshl_add_u64 v[130:131], s[4:5], 0, v[14:15]
	v_or_b32_e32 v15, 2, v0
	v_cmp_gt_u32_e64 s[12:13], v15, v116
	v_or_b32_e32 v15, 3, v0
	v_readlane_b32 s21, v247, 34
	v_cmp_gt_u32_e64 s[8:9], v0, v116
	v_cmp_lt_u32_e64 s[10:11], v0, v116
	v_cmp_gt_u32_e64 s[14:15], v15, v116
	v_mul_lo_u32 v15, v21, 48
	v_lshl_or_b32 v0, v22, 4, v0
	s_movk_i32 s2, 0xc4
	v_lshl_add_u32 v142, v12, 1, v2
	v_readlane_b32 s3, v247, 31
	v_lshl_add_u32 v159, v16, 1, s21
	v_lshlrev_b32_e32 v12, 3, v17
	v_lshlrev_b32_e32 v14, 4, v17
	v_or_b32_e32 v16, v15, v116
	v_add_u32_e32 v13, v15, v13
	v_add_u32_e32 v15, v15, v23
	v_mul_lo_u32 v0, v0, s2
	v_lshlrev_b32_e32 v31, 5, v116
	v_lshl_add_u32 v143, v20, 1, s3
	v_add_lshl_u32 v19, v0, v16, 1
	v_readlane_b32 s2, v247, 35
	v_add_u32_e32 v20, 0xc4, v0
	v_add_u32_e32 v23, 0x188, v0
	v_add_u32_e32 v25, 0x24c, v0
	v_add_lshl_u32 v27, v0, v13, 1
	v_add_lshl_u32 v0, v0, v15, 1
	v_lshl_or_b32 v31, v22, 11, v31
	v_readlane_b32 s25, v247, 36
	v_readlane_b32 s28, v247, 37
	v_add_u32_e32 v203, v2, v14
	v_add_u32_e32 v2, s21, v12
	v_readlane_b32 s21, v247, 38
	s_waitcnt lgkmcnt(0)
	s_barrier
; template <int MODE>
; __device__ void scan_unit(int swave, const Params& p, int j, int b, int h, int dir, char* shm) {
;     ...
;   f32x4 S[4][NVT];
; #pragma unroll
;   for (int a = 0; a < 4; ++a)
; #pragma unroll
;     for (int t = 0; t < NVT; ++t) S[a][t] = (f32x4){0.f, 0.f, 0.f, 0.f};
;   auto compute = [&](const char* buf, bf16_t* obuf) {
;     const bf16_t* qin = (const bf16_t*)buf; const bf16_t* ktil = (const bf16_t*)(buf + OFF_KT); const bf16_t* koutT = (const bf16_t*)(buf + OFF_KO);
;     const bf16_t* vT = (const bf16_t*)(buf + OFF_VT); const float* dec = (const float*)(buf + OFF_DEC);
;     bf16x8 Asc = {0, 0, 0, 0, 0, 0, 0, 0};
;     if (KS == 1 || wk == 0) {
;       f32x4 sc = {0.f, 0.f, 0.f, 0.f};
; #pragma unroll
;       for (int m = 0; m < DK / 32; ++m) {
;         const bf16x8 a = *(const bf16x8*)(ktil + r * QS + m * 32 + q4 * 8);
;         const bf16x8 bb = *(const bf16x8*)(qin + r * QS + m * 32 + q4 * 8);
;         sc = __builtin_amdgcn_mfma_f32_16x16x32_bf16(a, bb, sc, 0, 0, 0);
;       }
;       {
;         const unsigned p01 = pk2(q4 * 4 + 0 > r ? 0.f : sc[0], q4 * 4 + 1 > r ? 0.f : sc[1]);
;         const unsigned p23 = pk2(q4 * 4 + 2 > r ? 0.f : sc[2], q4 * 4 + 3 > r ? 0.f : sc[3]);
;         Asc[0] = (short)(p01 & 0xffff); Asc[1] = (short)(p01 >> 16); Asc[2] = (short)(p23 & 0xffff); Asc[3] = (short)(p23 >> 16);
;       }
;     }
;     bf16x8 Bv[NVT];
; #pragma unroll
;     for (int t = 0; t < NVT; ++t) {
;       const uint2 vv = *(const uint2*)(vT + ((vt0 + t) * 16 + r) * VS + q4 * 4);
;       Bv[t] = (bf16x8){(short)(vv.x & 0xffff), (short)(vv.x >> 16), (short)(vv.y & 0xffff), (short)(vv.y >> 16), 0, 0, 0, 0};
;     }
;     bf16x8 Aq[2];
; #pragma unroll
;     for (int m = 0; m < 2; ++m) {
;       const uint2 lo = *(const uint2*)(qin + r * QS + slab + (2 * m) * 16 + q4 * 4);
;       const uint2 hi = *(const uint2*)(qin + r * QS + slab + (2 * m + 1) * 16 + q4 * 4);
;       Aq[m] = (bf16x8){(short)(lo.x & 0xffff), (short)(lo.x >> 16), (short)(lo.y & 0xffff), (short)(lo.y >> 16),
;                        (short)(hi.x & 0xffff), (short)(hi.x >> 16), (short)(hi.y & 0xffff), (short)(hi.y >> 16)};
;     }
;     f32x4 o[NVT];
; #pragma unroll
;     for (int t = 0; t < NVT; ++t) {
;       o[t] = (f32x4){0.f, 0.f, 0.f, 0.f};
;       if (KS == 1 || wk == 0) o[t] = __builtin_amdgcn_mfma_f32_16x16x32_bf16(Asc, Bv[t], o[t], 0, 0, 0);
;     }
	v_lshlrev_b32_e32 v17, 7, v22
	v_add_lshl_u32 v21, v20, v16, 1
	v_add_lshl_u32 v28, v20, v13, 1
	v_add_u32_e32 v169, s2, v0
	v_add_lshl_u32 v20, v20, v15, 1
	v_add_u32_e32 v186, s25, v0
	v_add_u32_e32 v199, s28, v0
	v_add_u32_e32 v215, s21, v0
	v_add3_u32 v0, s3, v12, v31
	v_cmp_eq_u32_e64 s[6:7], 0, v22
	v_add_u32_e32 v160, v18, v14
	v_add_u32_e32 v18, 0, v17
	v_add_lshl_u32 v24, v23, v16, 1
	v_add_lshl_u32 v26, v25, v16, 1
	v_add_lshl_u32 v29, v23, v13, 1
	v_add_lshl_u32 v30, v25, v13, 1
	v_add_u32_e32 v170, s2, v20
	v_add_lshl_u32 v23, v23, v15, 1
	v_add_lshl_u32 v25, v25, v15, 1
	v_add_u32_e32 v32, 0, v12
	v_lshlrev_b32_e32 v22, 8, v22
	v_mul_lo_u32 v16, v16, 40
	v_mul_lo_u32 v13, v13, 40
	v_mul_lo_u32 v15, v15, 40
	v_add_u32_e32 v187, s25, v20
	v_add_u32_e32 v200, s28, v20
	v_add_u32_e32 v216, s21, v20
	v_add_u32_e32 v221, 0x200, v0
	v_add_u32_e32 v222, 0x400, v0
	v_add_u32_e32 v223, 0x600, v0
	v_lshlrev_b32_e32 v0, 3, v111
	v_mov_b32_e32 v20, 0
	s_mov_b32 s24, 0
	v_mov_b32_e32 v129, v128
	v_cmp_gt_i32_e64 s[4:5], s52, v111
	v_add_u32_e32 v161, s2, v19
	v_add_u32_e32 v162, s2, v21
	v_add_u32_e32 v163, s2, v24
	v_add_u32_e32 v164, s2, v26
	v_add_u32_e32 v165, s2, v27
	v_add_u32_e32 v166, s2, v28
	v_add_u32_e32 v167, s2, v29
	v_add_u32_e32 v168, s2, v30
	v_add_u32_e32 v171, s2, v23
	v_add_u32_e32 v172, s2, v25
	v_add_u32_e32 v173, v32, v31
	v_add3_u32 v174, 0, v22, v14
	v_add_u32_e32 v175, v32, v16
	v_add_u32_e32 v176, v32, v13
	v_add_u32_e32 v177, v32, v15
	v_add_u32_e32 v178, s25, v19
	v_add_u32_e32 v179, s25, v21
	v_add_u32_e32 v180, s25, v24
	v_add_u32_e32 v181, s25, v26
	v_add_u32_e32 v182, s25, v27
	v_add_u32_e32 v183, s25, v28
	v_add_u32_e32 v184, s25, v29
	v_add_u32_e32 v185, s25, v30
	v_add_u32_e32 v188, s25, v23
	v_add_u32_e32 v189, s25, v25
	v_add3_u32 v190, v18, v17, v14
	v_add_u32_e32 v191, s28, v19
	v_add_u32_e32 v192, s28, v21
	v_add_u32_e32 v193, s28, v24
	v_add_u32_e32 v194, s28, v26
	v_add_u32_e32 v195, s28, v27
	v_add_u32_e32 v196, s28, v28
	v_add_u32_e32 v197, s28, v29
	v_add_u32_e32 v198, s28, v30
	v_add_u32_e32 v201, s28, v23
	v_add_u32_e32 v202, s28, v25
	v_add_u32_e32 v204, v2, v16
	v_add_u32_e32 v205, v2, v13
	v_add_u32_e32 v206, v2, v15
	v_add_u32_e32 v207, s21, v19
	v_add_u32_e32 v208, s21, v21
	v_add_u32_e32 v209, s21, v24
	v_add_u32_e32 v210, s21, v26
	v_add_u32_e32 v211, s21, v27
	v_add_u32_e32 v212, s21, v28
	v_add_u32_e32 v213, s21, v29
	v_add_u32_e32 v214, s21, v30
	v_add_u32_e32 v217, s21, v23
	v_add_u32_e32 v218, s21, v25
	v_add3_u32 v219, s3, v31, v12
	v_add3_u32 v220, s20, v22, v14
	v_add3_u32 v224, v18, v1, v12
	v_add_u32_e32 v138, s28, v0
	v_add_u32_e32 v115, s21, v0
	v_add_u32_e32 v225, s2, v0
	v_add_u32_e32 v226, s25, v0
	v_mov_b32_e32 v21, v20
	v_mov_b32_e32 v22, v20
	v_mov_b32_e32 v23, v20
	v_mov_b32_e32 v32, v20
	v_mov_b32_e32 v33, v20
	v_mov_b32_e32 v34, v20
	v_mov_b32_e32 v35, v20
	v_mov_b32_e32 v36, v20
	v_mov_b32_e32 v37, v20
	v_mov_b32_e32 v38, v20
	v_mov_b32_e32 v39, v20
	v_mov_b32_e32 v44, v20
	v_mov_b32_e32 v45, v20
	v_mov_b32_e32 v46, v20
	v_mov_b32_e32 v47, v20
	v_mov_b32_e32 v48, v20
	v_mov_b32_e32 v49, v20
	v_mov_b32_e32 v50, v20
	v_mov_b32_e32 v51, v20
	v_mov_b32_e32 v52, v20
	v_mov_b32_e32 v53, v20
	v_mov_b32_e32 v54, v20
	v_mov_b32_e32 v55, v20
	v_mov_b32_e32 v56, v20
	v_mov_b32_e32 v57, v20
	v_mov_b32_e32 v58, v20
	v_mov_b32_e32 v59, v20
	v_mov_b32_e32 v60, v20
	v_mov_b32_e32 v61, v20
	v_mov_b32_e32 v62, v20
	v_mov_b32_e32 v63, v20
	v_mov_b32_e32 v64, v20
	v_mov_b32_e32 v65, v20
	v_mov_b32_e32 v66, v20
	v_mov_b32_e32 v67, v20
	v_mov_b32_e32 v40, v20
	v_mov_b32_e32 v41, v20
	v_mov_b32_e32 v42, v20
	v_mov_b32_e32 v43, v20
	v_mov_b32_e32 v28, v20
	v_mov_b32_e32 v29, v20
	v_mov_b32_e32 v30, v20
	v_mov_b32_e32 v31, v20
	v_mov_b32_e32 v24, v20
	v_mov_b32_e32 v25, v20
	v_mov_b32_e32 v26, v20
	v_mov_b32_e32 v27, v20
	s_waitcnt vmcnt(1)
	v_mov_b32_e32 v70, v4
	v_mov_b32_e32 v71, v6
	v_mov_b32_e32 v6, v5
	v_add_u32_e32 v227, 32, v143
	v_add_u32_e32 v228, 0x800, v143
	v_add_u32_e32 v229, 0x820, v143
	v_add_u32_e32 v230, 40, v159
	v_add_u32_e32 v231, 0x50, v159
	v_add_u32_e32 v232, 0x78, v159
	v_add_u32_e32 v233, 0xa0, v159
	v_add_u32_e32 v234, 0xc8, v159
	v_mov_b32_e32 v68, v113
	v_mov_b32_e32 v69, v114
	s_waitcnt vmcnt(0)
	v_mov_b32_e32 v0, v109
	v_mov_b32_e32 v1, v110
	v_lshlrev_b32_e32 v120, 2, v111
	v_readfirstlane_b32 vcc_lo, v147
	s_lshr_b32 vcc_lo, vcc_lo, 8
	s_cmp_eq_u32 vcc_lo, 0
	s_cbranch_scc1 .Lprio_skip0
	s_setprio 1
.Lprio_skip0:
	s_branch .LBB0_571
; __device__ __forceinline__ unsigned pk2(float lo, float hi) { f32x2_t v = {lo, hi}; bf16x2_t b = __builtin_convertvector(v, bf16x2_t); return __builtin_bit_cast(unsigned, b); }
; __device__ __forceinline__ bf16_t f2bf(float f) { return (bf16_t)(pk2(f, 0.f) & 0xffffu); }
; template <int MODE>
; __device__ void scan_unit(int swave, const Params& p, int j, int b, int h, int dir, char* shm) {
;     ...
;     for (int m = 0; m < 2; ++m)
; #pragma unroll
;       for (int t = 0; t < NVT; ++t) {
;         const f32x4 s0 = S[2 * m][t], s1 = S[2 * m + 1][t];
;         union { unsigned u[4]; bf16x8 v; } cv;
;         cv.u[0] = pk2(s0[0], s0[1]); cv.u[1] = pk2(s0[2], s0[3]); cv.u[2] = pk2(s1[0], s1[1]); cv.u[3] = pk2(s1[2], s1[3]);
;         o[t] = __builtin_amdgcn_mfma_f32_16x16x32_bf16(Aq[m], cv.v, o[t], 0, 0, 0);
;       }
; #pragma unroll
;     for (int t = 0; t < NVT; ++t)
; #pragma unroll
;       for (int jj = 0; jj < 4; ++jj) obuf[(wk * 16 + q4 * 4 + jj) * OS + (vt0 + t) * 16 + r] = f2bf(o[t][jj]);
; #pragma unroll
;     for (int kt = 0; kt < 4; ++kt) {
;       const uint2 kk = *(const uint2*)(koutT + (slab + kt * 16 + r) * 16 + q4 * 4);
;       const bf16x8 Ak = {(short)(kk.x & 0xffff), (short)(kk.x >> 16), (short)(kk.y & 0xffff), (short)(kk.y >> 16), 0, 0, 0, 0};
;       const f32x4 dc = *(const f32x4*)(dec + slab + kt * 16 + q4 * 4);
; #pragma unroll
;       for (int t = 0; t < NVT; ++t) S[kt][t] = __builtin_amdgcn_mfma_f32_16x16x32_bf16(Ak, Bv[t], S[kt][t] * dc, 0, 0, 0);
;     }
.LBB0_570:
	s_or_b64 exec, exec, s[2:3]
	s_waitcnt lgkmcnt(1)
	v_bfi_b32 v30, s30, v30, v30
	s_waitcnt lgkmcnt(0)
	v_bfi_b32 v26, s30, v26, v26
	v_cvt_pk_bf16_f32 v52, v96, v97
	v_cvt_pk_bf16_f32 v53, v98, v99
	v_cvt_pk_bf16_f32 v54, v20, v21
	v_cvt_pk_bf16_f32 v55, v22, v23
	s_add_i32 s24, s24, 2
	s_and_b64 vcc, exec, s[50:51]
	v_mfma_f32_16x16x32_bf16 v[44:47], v[28:31], v[52:55], v[44:47]
	v_cvt_pk_bf16_f32 v52, v92, v93
	v_cvt_pk_bf16_f32 v53, v94, v95
	v_cvt_pk_bf16_f32 v54, v12, v13
	v_cvt_pk_bf16_f32 v55, v14, v15
	s_nop 1
	v_mfma_f32_16x16x32_bf16 v[40:43], v[28:31], v[52:55], v[40:43]
	v_cvt_pk_bf16_f32 v52, v88, v89
	v_cvt_pk_bf16_f32 v53, v90, v91
	v_cvt_pk_bf16_f32 v54, v16, v17
	v_cvt_pk_bf16_f32 v55, v18, v19
	s_nop 1
	v_mfma_f32_16x16x32_bf16 v[28:31], v[28:31], v[52:55], v[48:51]
	s_nop 2
	v_cvt_pk_bf16_f32 v48, v68, v69
	v_cvt_pk_bf16_f32 v49, v70, v71
	v_cvt_pk_bf16_f32 v50, v80, v81
	v_cvt_pk_bf16_f32 v51, v82, v83
	s_nop 1
	v_mfma_f32_16x16x32_bf16 v[44:47], v[24:27], v[48:51], v[44:47]
	v_cvt_pk_bf16_f32 v48, v32, v33
	v_cvt_pk_bf16_f32 v49, v34, v35
	v_cvt_pk_bf16_f32 v50, v76, v77
	v_cvt_pk_bf16_f32 v51, v78, v79
	s_nop 1
	v_mfma_f32_16x16x32_bf16 v[40:43], v[24:27], v[48:51], v[40:43]
	v_cvt_pk_bf16_f32 v48, v36, v37
	v_cvt_pk_bf16_f32 v49, v38, v39
	v_cvt_pk_bf16_f32 v50, v72, v73
	v_cvt_pk_bf16_f32 v51, v74, v75
	s_nop 1
	v_mfma_f32_16x16x32_bf16 v[24:27], v[24:27], v[48:51], v[28:31]
	v_mov_b32_e32 v50, v3
	v_mov_b32_e32 v51, v3
	s_nop 0
	v_cvt_pk_bf16_f32 v28, v44, s0
	ds_write_b16 v207, v28
	v_cvt_pk_bf16_f32 v28, v45, s0
	ds_write_b16 v208, v28
	v_cvt_pk_bf16_f32 v28, v46, s0
	ds_write_b16 v209, v28
	v_cvt_pk_bf16_f32 v28, v47, s0
	ds_write_b16 v210, v28
	v_cvt_pk_bf16_f32 v28, v40, s0
	ds_write_b16 v211, v28
	v_cvt_pk_bf16_f32 v28, v41, s0
	ds_write_b16 v212, v28
	v_cvt_pk_bf16_f32 v28, v42, s0
	ds_write_b16 v213, v28
	v_cvt_pk_bf16_f32 v28, v43, s0
	v_cvt_pk_bf16_f32 v24, v24, s0
	ds_write_b16 v214, v28
	ds_write_b16 v215, v24
	v_cvt_pk_bf16_f32 v24, v25, s0
	ds_write_b16 v216, v24
	v_cvt_pk_bf16_f32 v24, v26, s0
	ds_write_b16 v217, v24
	v_cvt_pk_bf16_f32 v24, v27, s0
	ds_write_b16 v218, v24
	ds_read_b64 v[40:41], v219
	ds_read_b128 v[44:47], v220
	ds_read_b64 v[48:49], v221
	ds_read_b128 v[52:55], v220 offset:64
	v_mov_b32_e32 v42, v3
	v_mov_b32_e32 v43, v3
	ds_read_b128 v[84:87], v220 offset:192
	s_waitcnt lgkmcnt(3)
	v_pk_mul_f32 v[26:27], v[98:99], v[46:47]
	s_waitcnt lgkmcnt(1)
	v_pk_mul_f32 v[14:15], v[14:15], v[54:55]
	v_pk_mul_f32 v[12:13], v[12:13], v[52:53]
	v_pk_mul_f32 v[24:25], v[96:97], v[44:45]
	v_pk_mul_f32 v[30:31], v[94:95], v[46:47]
	v_mfma_f32_16x16x32_bf16 v[60:63], v[48:51], v[104:107], v[12:15]
	v_mul_f32_e64 v28, v92, v44
	v_mul_f32_e64 v29, v93, v45
	v_pk_mul_f32 v[46:47], v[90:91], v[46:47]
	v_pk_mul_f32 v[44:45], v[88:89], v[44:45]
	ds_read_b64 v[12:13], v222
	v_pk_mul_f32 v[22:23], v[22:23], v[54:55]
	v_pk_mul_f32 v[20:21], v[20:21], v[52:53]
	v_mfma_f32_16x16x32_bf16 v[24:27], v[40:43], v[0:3], v[24:27]
	v_mov_b32_e32 v14, v3
	v_mov_b32_e32 v15, v3
	v_pk_mul_f32 v[18:19], v[18:19], v[54:55]
	v_mfma_f32_16x16x32_bf16 v[28:31], v[40:43], v[104:107], v[28:31]
	v_mul_f32_e64 v16, v16, v52
	v_mul_f32_e64 v17, v17, v53
	v_mfma_f32_16x16x32_bf16 v[40:43], v[40:43], v[100:103], v[44:47]
	s_nop 2
	ds_read_b128 v[44:47], v220 offset:128
	v_mfma_f32_16x16x32_bf16 v[64:67], v[48:51], v[0:3], v[20:23]
	s_nop 2
	ds_read_b64 v[20:21], v223
	v_mov_b32_e32 v22, v3
	v_mov_b32_e32 v23, v3
	v_mfma_f32_16x16x32_bf16 v[56:59], v[48:51], v[100:103], v[16:19]
	s_waitcnt lgkmcnt(0)
	s_barrier
	s_waitcnt lgkmcnt(1)
	s_nop 0
	v_pk_mul_f32 v[18:19], v[70:71], v[46:47]
	v_pk_mul_f32 v[16:17], v[68:69], v[44:45]
	s_waitcnt vmcnt(6)
	v_mov_b32_e32 v68, v113
	v_mov_b32_e32 v69, v114
	v_mfma_f32_16x16x32_bf16 v[52:55], v[12:15], v[0:3], v[16:19]
	s_waitcnt vmcnt(1)
	v_mov_b32_e32 v70, v4
	v_mov_b32_e32 v71, v6
	v_mov_b32_e32 v6, v5
	v_pk_mul_f32 v[18:19], v[34:35], v[46:47]
	v_pk_mul_f32 v[16:17], v[32:33], v[44:45]
	s_nop 1
	v_mfma_f32_16x16x32_bf16 v[48:51], v[12:15], v[104:107], v[16:19]
	s_nop 2
	v_mul_f32_e64 v18, v38, v46
	v_mul_f32_e64 v19, v39, v47
	v_pk_mul_f32 v[16:17], v[36:37], v[44:45]
	s_nop 1
	v_mfma_f32_16x16x32_bf16 v[44:47], v[12:15], v[100:103], v[16:19]
	v_mul_f32_e64 v14, v82, v86
	v_mul_f32_e64 v15, v83, v87
	v_pk_mul_f32 v[12:13], v[80:81], v[84:85]
	s_waitcnt lgkmcnt(0)
	s_nop 0
	v_mfma_f32_16x16x32_bf16 v[36:39], v[20:23], v[0:3], v[12:15]
	s_waitcnt vmcnt(0)
	v_mov_b32_e32 v0, v109
	v_mov_b32_e32 v1, v110
	v_pk_mul_f32 v[14:15], v[78:79], v[86:87]
	v_pk_mul_f32 v[12:13], v[76:77], v[84:85]
	s_nop 1
	v_mfma_f32_16x16x32_bf16 v[32:35], v[20:23], v[104:107], v[12:15]
	s_nop 2
	v_mul_f32_e64 v14, v74, v86
	v_mul_f32_e64 v15, v75, v87
	v_pk_mul_f32 v[12:13], v[72:73], v[84:85]
	s_nop 1
	v_mfma_f32_16x16x32_bf16 v[20:23], v[20:23], v[100:103], v[12:15]
	s_cbranch_vccnz .LBB0_621

; __device__ __forceinline__ unsigned pk2(float lo, float hi) { f32x2_t v = {lo, hi}; bf16x2_t b = __builtin_convertvector(v, bf16x2_t); return __builtin_bit_cast(unsigned, b); }
; __device__ __forceinline__ float lo_bf(unsigned u) { return __uint_as_float(u << 16); }
; __device__ __forceinline__ float hi_bf(unsigned u) { return __uint_as_float(u & 0xffff0000u); }
; template <int MODE>
; __device__ void scan_unit(int swave, const Params& p, int j, int b, int h, int dir, char* shm) {
;     ...
;   auto ostore = [&](int c, const bf16_t* obuf) {
;     for (int idx = tid; idx < 16 * DV / 4; idx += 512) {
;       const int i = idx / (DV / 4), cc = (idx % (DV / 4)) * 4;
;       uint2 o = *(const uint2*)(obuf + i * OS + cc);
;       if (KS == 2) {
;         const uint2 o2 = *(const uint2*)(obuf + (16 + i) * OS + cc);
;         o.x = pk2(lo_bf(o.x) + lo_bf(o2.x), hi_bf(o.x) + hi_bf(o2.x)); o.y = pk2(lo_bf(o.y) + lo_bf(o2.y), hi_bf(o.y) + hi_bf(o2.y));
;       }
;       *(uint2*)(O + (rowbase + tokof(c, i)) * OLD + cc) = o;
;     }
;     ...
;   ostore(NCH - 2, obp((NIT - 1) & 1, 0)); ostore(NCH - 1, obp((NIT - 1) & 1, 1));
.LBB0_621:
	s_setprio 0
	s_and_saveexec_b64 s[2:3], s[4:5]
	s_movk_i32 s8, 0x600
	s_cbranch_execz .LBB0_626
	s_mov_b64 s[4:5], 0
	v_mov_b32_e32 v0, v120
	v_mov_b32_e32 v1, v111

; template <int MODE>
; __device__ void scan_unit(int swave, const Params& p, int j, int b, int h, int dir, char* shm) {
;     ...
;   auto load_raw = [&](int c, Raw& R) {
;     const int tok = tokof(c, ti);
;     const bf16_t* row = P + (rowbase + tok) * LDP;
;     if (MODE == 0) {
;       R.q = *(const unsigned*)(row + E_GQ + h * 64 + dp); R.k = *(const unsigned*)(row + E_GK + h * 64 + dp);
;       const uint4* lrp = (const uint4*)(row + (dir ? E_GLB : E_GLF));
;       R.lr0 = lrp[0]; R.lr1 = lrp[1];
;       R.v = *(const uint2*)(row + E_GV + h * 128 + vg * 4);
;     } else if (MODE == 1) {
;       R.q = *(const unsigned*)(row + E_HQ + h * 64 + dp); R.k = *(const unsigned*)(row + (dir ? E_HZB : E_HZF) + h * 64 + dp);
;       R.v = *(const uint2*)(row + E_HI + h * 128 + vg * 4);
;     ...
;       const unsigned v0 = R.v.x, v1 = R.v.y; const int c4 = vg * 4;
;       vT[(c4 + 0) * VS + ti] = (bf16_t)(v0 & 0xffff); vT[(c4 + 1) * VS + ti] = (bf16_t)(v0 >> 16);
;       vT[(c4 + 2) * VS + ti] = (bf16_t)(v1 & 0xffff); vT[(c4 + 3) * VS + ti] = (bf16_t)(v1 >> 16);
;     } else {
;       const float KSC = 0.08838834764831845f;
;       const float qx0 = lo_bf(R.q), qx1 = hi_bf(R.q), qy0 = lo_bf(R.q2), qy1 = hi_bf(R.q2);
;       const float kx0 = lo_bf(R.k) * KSC, kx1 = hi_bf(R.k) * KSC, ky0 = lo_bf(R.k2) * KSC, ky1 = hi_bf(R.k2) * KSC;
;       const float c0 = R.cs.x, sn0 = R.cs.y, c1 = R.cs.z, sn1 = R.cs.w;
;       const float qa0 = qx0 * c0 - qy0 * sn0, qb0 = qx0 * sn0 + qy0 * c0, qa1 = qx1 * c1 - qy1 * sn1, qb1 = qx1 * sn1 + qy1 * c1;
;       const float ka0 = kx0 * c0 - ky0 * sn0, kb0 = kx0 * sn0 + ky0 * c0, ka1 = kx1 * c1 - ky1 * sn1, kb1 = kx1 * sn1 + ky1 * c1;
;       const float ein = ret_ein, eti = ret_eti, eout = ret_eout;
;       *(unsigned*)(qin + ti * QS + dp) = pk2(qa0 * ein, qa1 * ein); *(unsigned*)(qin + ti * QS + 64 + dp) = pk2(qb0 * ein, qb1 * ein);
;       *(unsigned*)(ktil + ti * QS + dp) = pk2(ka0 * eti, ka1 * eti); *(unsigned*)(ktil + ti * QS + 64 + dp) = pk2(kb0 * eti, kb1 * eti);
;       koutT[dp * 16 + ti] = f2bf(ka0 * eout); koutT[(dp + 1) * 16 + ti] = f2bf(ka1 * eout);
;       koutT[(64 + dp) * 16 + ti] = f2bf(kb0 * eout); koutT[(65 + dp) * 16 + ti] = f2bf(kb1 * eout);
;       if (ti == 0) { const float dd = ret_dd; *(float2*)(dec + dp) = make_float2(dd, dd); *(float2*)(dec + 64 + dp) = make_float2(dd, dd); }
;       const int c6 = vg * 6;
.LBB0_645:
	s_or_b64 exec, exec, s[4:5]
	v_readlane_b32 s4, v248, 8
	v_readlane_b32 s6, v248, 10
	v_readlane_b32 s5, v248, 9
	v_readlane_b32 s7, v248, 11
	s_add_u32 s4, s6, s2
	s_addc_u32 s5, s7, s3
	v_or_b32_e32 v0, 32, v37
	v_xor_b32_e32 v2, 0x7df, v37
	s_and_b64 s[2:3], s[0:1], exec
	v_cndmask_b32_e64 v0, v2, v0, s[0:1]
	s_cselect_b32 s2, 0, 0x4000000
	v_or_b32_e32 v0, s46, v0
	v_mov_b64_e32 v[6:7], s[48:49]
	s_add_u32 s4, s4, s2
	v_mad_u64_u32 v[10:11], s[2:3], v0, s53, v[6:7]
	v_or_b32_e32 v0, 48, v37
	v_xor_b32_e32 v2, 0x7cf, v37
	v_cndmask_b32_e64 v0, v2, v0, s[0:1]
	s_addc_u32 s5, s5, 0
	s_lshl_b32 s70, s8, 1
	v_or_b32_e32 v0, s46, v0
	s_mov_b32 s72, s70
	s_mov_b32 s73, s95
	v_mad_i32_i24 v11, s47, v156, v11
	v_mad_u64_u32 v[6:7], s[2:3], v0, s53, v[6:7]
	v_lshl_add_u64 v[12:13], v[10:11], 0, s[50:51]
	v_lshl_add_u64 v[14:15], v[10:11], 0, s[94:95]
	v_lshl_add_u64 v[10:11], v[10:11], 0, s[72:73]
	v_mad_i32_i24 v7, s47, v156, v7
	v_lshl_add_u64 v[10:11], v[10:11], 0, v[26:27]
	v_lshl_add_u64 v[18:19], v[6:7], 0, s[94:95]
	v_lshl_add_u64 v[12:13], v[12:13], 0, v[22:23]
	v_lshl_add_u64 v[14:15], v[14:15], 0, s[50:51]
	v_add_co_u32_e32 v10, vcc, s62, v10
	v_lshl_add_u64 v[16:17], v[6:7], 0, s[50:51]
	v_lshl_add_u64 v[18:19], v[18:19], 0, s[50:51]
	v_lshl_add_u64 v[6:7], v[6:7], 0, s[72:73]
	v_lshl_add_u64 v[14:15], v[14:15], 0, v[22:23]
	v_addc_co_u32_e32 v11, vcc, 0, v11, vcc
	v_lshl_add_u64 v[16:17], v[16:17], 0, v[22:23]
	v_lshl_add_u64 v[18:19], v[18:19], 0, v[22:23]
	global_load_dword v57, v[12:13], off offset:3136
	global_load_dword v59, v[14:15], off
	global_load_dwordx2 v[30:31], v[10:11], off offset:576
	global_load_dword v54, v[16:17], off offset:3136
	global_load_dword v55, v[18:19], off
	v_lshl_add_u64 v[6:7], v[6:7], 0, v[26:27]
	v_add_co_u32_e32 v6, vcc, s62, v6
	v_lshrrev_b32_e32 v0, 4, v1
	s_nop 0
	v_addc_co_u32_e32 v7, vcc, 0, v7, vcc
	global_load_dwordx2 v[28:29], v[6:7], off offset:576
	s_add_u32 s2, s4, s70
	s_waitcnt vmcnt(6)
	ds_write_b16 v42, v4 offset:18688
	ds_write_b16_d16_hi v42, v4 offset:18728
	ds_write_b16 v42, v5 offset:18768
	ds_write_b16_d16_hi v42, v5 offset:18808
	v_lshlrev_b32_e32 v4, 2, v0
	s_addc_u32 s3, s5, 0
	v_cmp_gt_u32_e64 s[6:7], v4, v37
	v_cmp_lt_u32_e64 s[8:9], v4, v37
	v_or_b32_e32 v5, 2, v4
	v_or_b32_e32 v4, 3, v4
	s_add_u32 s68, s2, 0x4000400
	s_movk_i32 s2, 0x200
	v_cmp_gt_u32_e64 s[12:13], v4, v37
	v_ashrrev_i32_e32 v4, 2, v36
	v_cmp_gt_i32_e64 s[4:5], s2, v36
	v_and_or_b32 v4, v4, -16, v37
	s_movk_i32 s2, 0x210
	v_lshlrev_b32_e32 v2, 3, v0
	v_mad_u32_u24 v0, v0, s2, v4
	v_lshl_add_u32 v48, v0, 1, 0
	v_lshlrev_b32_e32 v0, 5, v37
	v_add3_u32 v49, 0, v0, v2
	v_lshlrev_b32_e32 v0, 3, v36
	v_readlane_b32 s2, v247, 39
	s_waitcnt lgkmcnt(0)
	s_barrier
	v_and_b32_e32 v1, 48, v1
	v_add_u32_e32 v45, s2, v0
	v_readlane_b32 s2, v247, 40
	v_cmp_gt_u32_e64 s[10:11], v5, v37
	v_mul_lo_u32 v5, v4, 40
	v_add_u32_e32 v44, s2, v0
	v_readlane_b32 s2, v247, 41
	v_add_u32_e32 v46, v8, v1
	v_add3_u32 v47, 0, v5, v2
	v_sub_u32_e32 v5, 0, v2
	v_add_u32_e32 v51, s2, v0
	v_readlane_b32 s2, v247, 42
	v_mov_b32_e32 v4, 0
	s_mov_b32 s35, 0
	s_addc_u32 s69, s3, 0
	v_add_u32_e32 v50, 0, v1
	v_lshlrev_b32_e32 v43, 2, v36
	v_add_u32_e32 v52, s2, v0
	v_add_u32_e32 v53, v46, v5
	v_mov_b32_e32 v5, v4
	v_mov_b32_e32 v6, v4
	v_mov_b32_e32 v7, v4
	v_mov_b32_e32 v8, v4
	v_mov_b32_e32 v9, v4
	v_mov_b32_e32 v10, v4
	v_mov_b32_e32 v11, v4
	v_mov_b32_e32 v12, v4
	v_mov_b32_e32 v13, v4
	v_mov_b32_e32 v14, v4
	v_mov_b32_e32 v15, v4
	v_mov_b32_e32 v16, v4
	v_mov_b32_e32 v17, v4
	v_mov_b32_e32 v18, v4
	v_mov_b32_e32 v19, v4
	v_readfirstlane_b32 vcc_lo, v147
	s_lshr_b32 vcc_lo, vcc_lo, 8
	s_cmp_eq_u32 vcc_lo, 0
	s_cbranch_scc1 .Lprio_skip1
	s_setprio 1
.Lprio_skip1:
	s_branch .LBB0_647
; template <int MODE>
; __device__ void scan_unit(int swave, const Params& p, int j, int b, int h, int dir, char* shm) {
;     ...
;   auto compute = [&](const char* buf, bf16_t* obuf) {
;     const bf16_t* qin = (const bf16_t*)buf; const bf16_t* ktil = (const bf16_t*)(buf + OFF_KT); const bf16_t* koutT = (const bf16_t*)(buf + OFF_KO);
;     const bf16_t* vT = (const bf16_t*)(buf + OFF_VT); const float* dec = (const float*)(buf + OFF_DEC);
;     bf16x8 Asc = {0, 0, 0, 0, 0, 0, 0, 0};
;     if (KS == 1 || wk == 0) {
;       f32x4 sc = {0.f, 0.f, 0.f, 0.f};
; #pragma unroll
;       for (int m = 0; m < DK / 32; ++m) {
;         const bf16x8 a = *(const bf16x8*)(ktil + r * QS + m * 32 + q4 * 8);
;         const bf16x8 bb = *(const bf16x8*)(qin + r * QS + m * 32 + q4 * 8);
;         sc = __builtin_amdgcn_mfma_f32_16x16x32_bf16(a, bb, sc, 0, 0, 0);
;       }
;       {
;         const unsigned p01 = pk2(q4 * 4 + 0 > r ? 0.f : sc[0], q4 * 4 + 1 > r ? 0.f : sc[1]);
;         const unsigned p23 = pk2(q4 * 4 + 2 > r ? 0.f : sc[2], q4 * 4 + 3 > r ? 0.f : sc[3]);
;         Asc[0] = (short)(p01 & 0xffff); Asc[1] = (short)(p01 >> 16); Asc[2] = (short)(p23 & 0xffff); Asc[3] = (short)(p23 >> 16);
;       }
;     }
;     bf16x8 Bv[NVT];
; #pragma unroll
;     for (int t = 0; t < NVT; ++t) {
;       const uint2 vv = *(const uint2*)(vT + ((vt0 + t) * 16 + r) * VS + q4 * 4);
;       Bv[t] = (bf16x8){(short)(vv.x & 0xffff), (short)(vv.x >> 16), (short)(vv.y & 0xffff), (short)(vv.y >> 16), 0, 0, 0, 0};
;     }
;     bf16x8 Aq[2];
; #pragma unroll
;     for (int m = 0; m < 2; ++m) {
;       const uint2 lo = *(const uint2*)(qin + r * QS + slab + (2 * m) * 16 + q4 * 4);
;       const uint2 hi = *(const uint2*)(qin + r * QS + slab + (2 * m + 1) * 16 + q4 * 4);
;       Aq[m] = (bf16x8){(short)(lo.x & 0xffff), (short)(lo.x >> 16), (short)(lo.y & 0xffff), (short)(lo.y >> 16),
;                        (short)(hi.x & 0xffff), (short)(hi.x >> 16), (short)(hi.y & 0xffff), (short)(hi.y >> 16)};
;     }
;     f32x4 o[NVT];
; #pragma unroll
;     for (int t = 0; t < NVT; ++t) {
;       o[t] = (f32x4){0.f, 0.f, 0.f, 0.f};
;       if (KS == 1 || wk == 0) o[t] = __builtin_amdgcn_mfma_f32_16x16x32_bf16(Asc, Bv[t], o[t], 0, 0, 0);
;     }
; #pragma unroll
;     for (int m = 0; m < 2; ++m)
; #pragma unroll
;       for (int t = 0; t < NVT; ++t) {
;         const f32x4 s0 = S[2 * m][t], s1 = S[2 * m + 1][t];
.LBB0_646:
	s_or_b64 exec, exec, s[2:3]
	ds_write_b16 v42, v32 offset:18688
	ds_write_b16_d16_hi v42, v32 offset:18728
	ds_write_b16 v42, v33 offset:18768
	ds_write_b16_d16_hi v42, v33 offset:18808
	ds_read_b128 v[32:35], v46 offset:26368
	ds_read_b128 v[64:67], v46 offset:24064
	ds_read_b128 v[68:71], v46 offset:26432
	ds_read_b128 v[72:75], v46 offset:24128
	v_add_u32_e32 v0, 0x5800, v53
	v_add_u32_e32 v56, 0x8800, v53
	s_waitcnt lgkmcnt(2)
	v_mfma_f32_16x16x32_bf16 v[32:35], v[32:35], v[64:67], 0
	ds_read_b64 v[64:65], v47 offset:30720
	ds_read2_b64 v[76:79], v0 offset0:192 offset1:196
	ds_read2_b64 v[80:83], v0 offset0:200 offset1:204
	v_mov_b32_e32 v66, v3
	v_mov_b32_e32 v67, v3
	s_waitcnt lgkmcnt(3)
	v_mfma_f32_16x16x32_bf16 v[32:35], v[68:71], v[72:75], v[32:35]
	s_waitcnt lgkmcnt(1)
	v_bfi_b32 v78, s30, v78, v78
	s_waitcnt lgkmcnt(0)
	v_bfi_b32 v82, s30, v82, v82
	v_cvt_pk_bf16_f32 v68, v8, v9
	v_cvt_pk_bf16_f32 v69, v10, v11
	v_cvt_pk_bf16_f32 v70, v12, v13
	s_nop 0
	v_cndmask_b32_e64 v0, v32, 0, s[6:7]
	v_cndmask_b32_e64 v1, 0, v33, s[8:9]
	v_cndmask_b32_e64 v2, v34, 0, s[10:11]
	v_cndmask_b32_e64 v32, v35, 0, s[12:13]
	v_cvt_pk_bf16_f32 v0, v0, v1
	v_cvt_pk_bf16_f32 v1, v2, v32
	v_mov_b32_e32 v2, v3
	v_cvt_pk_bf16_f32 v71, v14, v15
	s_add_i32 s35, s35, 2
	v_mfma_f32_16x16x32_bf16 v[32:35], v[0:3], v[64:67], 0
	s_and_b64 vcc, exec, s[74:75]
	v_mfma_f32_16x16x32_bf16 v[32:35], v[76:79], v[68:71], v[32:35]
	v_cvt_pk_bf16_f32 v68, v16, v17
	v_cvt_pk_bf16_f32 v69, v18, v19
	v_cvt_pk_bf16_f32 v70, v4, v5
	v_cvt_pk_bf16_f32 v71, v6, v7
	s_nop 1
	v_mfma_f32_16x16x32_bf16 v[32:35], v[80:83], v[68:71], v[32:35]
	s_nop 7
	v_cvt_pk_bf16_f32 v0, v32, s0
	ds_write_b16 v48, v0 offset:56576
	v_cvt_pk_bf16_f32 v0, v33, s0
	ds_write_b16 v48, v0 offset:56840
	v_cvt_pk_bf16_f32 v0, v34, s0
	ds_write_b16 v48, v0 offset:57104
	v_cvt_pk_bf16_f32 v0, v35, s0
	ds_write_b16 v48, v0 offset:57368
	ds_read2st64_b64 v[32:35], v49 offset0:56 offset1:57
	ds_read2st64_b64 v[68:71], v49 offset0:58 offset1:59
	ds_read_b128 v[72:75], v50 offset:35840
	ds_read_b128 v[76:79], v50 offset:35904
	s_waitcnt lgkmcnt(3)
	v_mov_b32_e32 v0, v32
	v_mov_b32_e32 v1, v33
	s_waitcnt lgkmcnt(1)
	v_pk_mul_f32 v[10:11], v[10:11], v[74:75]
	v_pk_mul_f32 v[8:9], v[8:9], v[72:73]
	s_waitcnt lgkmcnt(0)
	v_pk_mul_f32 v[14:15], v[14:15], v[78:79]
	v_pk_mul_f32 v[12:13], v[12:13], v[76:77]
	v_mfma_f32_16x16x32_bf16 v[8:11], v[0:3], v[64:67], v[8:11]
	v_mov_b32_e32 v0, v34
	v_mov_b32_e32 v1, v35
	ds_read_b128 v[32:35], v50 offset:35968
	ds_read_b128 v[72:75], v50 offset:36032
	v_mfma_f32_16x16x32_bf16 v[12:15], v[0:3], v[64:67], v[12:15]
	v_mov_b32_e32 v0, v68
	v_mov_b32_e32 v1, v69
	s_waitcnt lgkmcnt(1)
	v_pk_mul_f32 v[18:19], v[18:19], v[34:35]
	v_pk_mul_f32 v[16:17], v[16:17], v[32:33]
	v_cvt_pk_bf16_f32 v76, v8, v9
	v_cvt_pk_bf16_f32 v77, v10, v11
	v_mfma_f32_16x16x32_bf16 v[32:35], v[0:3], v[64:67], v[16:19]
	v_mov_b32_e32 v0, v70
	v_mov_b32_e32 v1, v71
	v_cvt_pk_bf16_f32 v78, v12, v13
	ds_read_b128 v[16:19], v46 offset:38400
	s_waitcnt lgkmcnt(1)
	v_pk_mul_f32 v[6:7], v[6:7], v[74:75]
	v_pk_mul_f32 v[4:5], v[4:5], v[72:73]
	v_cvt_pk_bf16_f32 v79, v14, v15
	s_nop 0
	v_mfma_f32_16x16x32_bf16 v[4:7], v[0:3], v[64:67], v[4:7]
	ds_read_b128 v[64:67], v46 offset:38464
	ds_read_b128 v[68:71], v46 offset:36096
	ds_read_b128 v[72:75], v46 offset:36160
	s_waitcnt lgkmcnt(1)
	v_mfma_f32_16x16x32_bf16 v[16:19], v[16:19], v[68:71], 0
	v_mov_b32_e32 v70, v3
	v_mov_b32_e32 v71, v3
	s_waitcnt lgkmcnt(0)
	v_mfma_f32_16x16x32_bf16 v[16:19], v[64:67], v[72:75], v[16:19]
	s_nop 7
	v_cndmask_b32_e64 v0, v16, 0, s[6:7]
	v_cndmask_b32_e64 v1, 0, v17, s[8:9]
	v_cvt_pk_bf16_f32 v0, v0, v1
	v_cndmask_b32_e64 v1, v18, 0, s[10:11]
	v_cndmask_b32_e64 v2, v19, 0, s[12:13]
	ds_read2_b64 v[16:19], v56 offset0:160 offset1:164
	ds_read2_b64 v[64:67], v56 offset0:168 offset1:172
	v_cvt_pk_bf16_f32 v1, v1, v2
	ds_read_b64 v[68:69], v47 offset:42752
	v_mov_b32_e32 v2, v3
	s_waitcnt lgkmcnt(2)
	v_bfi_b32 v18, s30, v18, v18
	s_waitcnt lgkmcnt(1)
	v_bfi_b32 v66, s30, v66, v66
	s_waitcnt lgkmcnt(0)
	v_mfma_f32_16x16x32_bf16 v[72:75], v[0:3], v[68:71], 0
	v_mfma_f32_16x16x32_bf16 v[16:19], v[16:19], v[76:79], v[72:75]
	s_nop 6
	v_cvt_pk_bf16_f32 v72, v32, v33
	v_cvt_pk_bf16_f32 v73, v34, v35
	v_cvt_pk_bf16_f32 v74, v4, v5
	v_cvt_pk_bf16_f32 v75, v6, v7
	s_nop 1
	v_mfma_f32_16x16x32_bf16 v[16:19], v[64:67], v[72:75], v[16:19]
	s_nop 7
	v_cvt_pk_bf16_f32 v0, v16, s0
	ds_write_b16 v48, v0 offset:60800
	v_cvt_pk_bf16_f32 v0, v17, s0
	ds_write_b16 v48, v0 offset:61064
	v_cvt_pk_bf16_f32 v0, v18, s0
	ds_write_b16 v48, v0 offset:61328
	v_cvt_pk_bf16_f32 v0, v19, s0
	ds_write_b16 v48, v0 offset:61592
	ds_read2st64_b64 v[64:67], v62 offset0:79 offset1:80
	ds_read2st64_b64 v[60:63], v62 offset0:81 offset1:82
	ds_read_b128 v[16:19], v50 offset:47872
	ds_read_b128 v[72:75], v50 offset:47936
	s_waitcnt lgkmcnt(3)
	v_mov_b32_e32 v0, v64
	v_mov_b32_e32 v1, v65
	s_waitcnt lgkmcnt(1)
	v_pk_mul_f32 v[10:11], v[10:11], v[18:19]
	v_pk_mul_f32 v[8:9], v[8:9], v[16:17]
	s_nop 1
	v_mfma_f32_16x16x32_bf16 v[16:19], v[0:3], v[68:71], v[8:11]
	v_mov_b32_e32 v0, v66
	v_mov_b32_e32 v1, v67
	ds_read_b128 v[64:67], v50 offset:48064
	s_waitcnt lgkmcnt(1)
	v_pk_mul_f32 v[10:11], v[14:15], v[74:75]
	v_pk_mul_f32 v[8:9], v[12:13], v[72:73]
	s_waitcnt lgkmcnt(0)
	v_pk_mul_f32 v[6:7], v[6:7], v[66:67]
	v_mfma_f32_16x16x32_bf16 v[12:15], v[0:3], v[68:71], v[8:11]
	v_mov_b32_e32 v0, v60
	v_mov_b32_e32 v1, v61
	v_pk_mul_f32 v[4:5], v[4:5], v[64:65]
	ds_read_b128 v[8:11], v50 offset:48000
	s_waitcnt lgkmcnt(0)
	s_barrier
	s_waitcnt lgkmcnt(0)
	v_pk_mul_f32 v[10:11], v[34:35], v[10:11]
	v_pk_mul_f32 v[8:9], v[32:33], v[8:9]
	s_nop 1
	v_mfma_f32_16x16x32_bf16 v[8:11], v[0:3], v[68:71], v[8:11]
	v_mov_b32_e32 v0, v62
	v_mov_b32_e32 v1, v63
	s_nop 1
	v_mfma_f32_16x16x32_bf16 v[4:7], v[0:3], v[68:71], v[4:7]
	s_cbranch_vccnz .LBB0_665

; __device__ __forceinline__ unsigned pk2(float lo, float hi) { f32x2_t v = {lo, hi}; bf16x2_t b = __builtin_convertvector(v, bf16x2_t); return __builtin_bit_cast(unsigned, b); }
; __device__ __forceinline__ float lo_bf(unsigned u) { return __uint_as_float(u << 16); }
; __device__ __forceinline__ float hi_bf(unsigned u) { return __uint_as_float(u & 0xffff0000u); }
; template <int MODE>
; __device__ void scan_unit(int swave, const Params& p, int j, int b, int h, int dir, char* shm) {
;     ...
;   auto ostore = [&](int c, const bf16_t* obuf) {
;     for (int idx = tid; idx < 16 * DV / 4; idx += 512) {
;       const int i = idx / (DV / 4), cc = (idx % (DV / 4)) * 4;
;       uint2 o = *(const uint2*)(obuf + i * OS + cc);
;       if (KS == 2) {
;         const uint2 o2 = *(const uint2*)(obuf + (16 + i) * OS + cc);
;         o.x = pk2(lo_bf(o.x) + lo_bf(o2.x), hi_bf(o.x) + hi_bf(o2.x)); o.y = pk2(lo_bf(o.y) + lo_bf(o2.y), hi_bf(o.y) + hi_bf(o2.y));
;       }
;       *(uint2*)(O + (rowbase + tokof(c, i)) * OLD + cc) = o;
;     }
.LBB0_665:
	s_setprio 0
	s_and_saveexec_b64 s[2:3], s[4:5]
	s_cbranch_execz .LBB0_670
	s_mov_b64 s[4:5], 0
	v_mov_b32_e32 v0, v43
	v_mov_b32_e32 v1, v36

; template <int MODE>
; __device__ void scan_unit(int swave, const Params& p, int j, int b, int h, int dir, char* shm) {
;     ...
;   auto load_raw = [&](int c, Raw& R) {
;     const int tok = tokof(c, ti);
;     const bf16_t* row = P + (rowbase + tok) * LDP;
;     if (MODE == 0) {
;       R.q = *(const unsigned*)(row + E_GQ + h * 64 + dp); R.k = *(const unsigned*)(row + E_GK + h * 64 + dp);
;       const uint4* lrp = (const uint4*)(row + (dir ? E_GLB : E_GLF));
;       R.lr0 = lrp[0]; R.lr1 = lrp[1];
;       R.v = *(const uint2*)(row + E_GV + h * 128 + vg * 4);
;     } else if (MODE == 1) {
;       R.q = *(const unsigned*)(row + E_HQ + h * 64 + dp); R.k = *(const unsigned*)(row + (dir ? E_HZB : E_HZF) + h * 64 + dp);
;       R.v = *(const uint2*)(row + E_HI + h * 128 + vg * 4);
;     } else {
;       R.q = *(const unsigned*)(row + O_RQ + h * 128 + dp); R.q2 = *(const unsigned*)(row + O_RQ + h * 128 + 64 + dp);
;       R.k = *(const unsigned*)(row + O_RK + h * 128 + dp); R.k2 = *(const unsigned*)(row + O_RK + h * 128 + 64 + dp);
;       R.cs = *(const float4*)(rope + tok * 64 + dp);
;       const unsigned* vp = (const unsigned*)(row + O_RV + h * 192 + vg * 6);
;       R.v30 = vp[0]; R.v31 = vp[1]; R.v32 = vp[2];
;     }
;   };
;   auto row_scan = [&](float x, float& total) {
;     x += __int_as_float(__builtin_amdgcn_update_dpp(0, __float_as_int(x), 0x111, 0xf, 0xf, true));
;     x += __int_as_float(__builtin_amdgcn_update_dpp(0, __float_as_int(x), 0x112, 0xf, 0xf, true));
;     x += __int_as_float(__builtin_amdgcn_update_dpp(0, __float_as_int(x), 0x114, 0xf, 0xf, true));
;     x += __int_as_float(__builtin_amdgcn_update_dpp(0, __float_as_int(x), 0x118, 0xf, 0xf, true));
;     total = __int_as_float(__builtin_amdgcn_ds_bpermute((lane | 15) << 2, __float_as_int(x)));
;     return x;
;   };
;   auto stage2 = [&](const Raw& R, char* buf, int c) {
;     bf16_t* qin = (bf16_t*)buf; bf16_t* ktil = (bf16_t*)(buf + OFF_KT); bf16_t* koutT = (bf16_t*)(buf + OFF_KO);
;     bf16_t* vT = (bf16_t*)(buf + OFF_VT); float* dec = (float*)(buf + OFF_DEC);
;     if (MODE != 2) {
;       float g0, g1;
;       if (MODE == 0) {
;         float z0 = bav0, z1 = bav1;
;         const unsigned lw[8] = {R.lr0.x, R.lr0.y, R.lr0.z, R.lr0.w, R.lr1.x, R.lr1.y, R.lr1.z, R.lr1.w};
; #pragma unroll
;         for (int e = 0; e < 8; ++e) {
;           const float a0 = lo_bf(lw[e]), a1 = hi_bf(lw[e]);
.LBB0_675:
	s_or_b64 exec, exec, s[4:5]
	v_readlane_b32 s8, v248, 8
	v_readlane_b32 s10, v248, 10
	v_readlane_b32 s11, v248, 11
	s_add_u32 s4, s10, s2
	s_addc_u32 s5, s11, s3
	s_and_b64 s[2:3], s[0:1], exec
	s_cselect_b32 s2, 0, 0x4000000
	s_add_u32 s2, s4, s2
	s_addc_u32 s3, s5, 0
	s_lshl_b32 s50, s94, 1
	s_add_u32 s2, s2, s50
	v_or_b32_e32 v4, 32, v99
	v_xor_b32_e32 v5, 0x7df, v99
	s_addc_u32 s3, s3, 0
	v_cndmask_b32_e64 v4, v5, v4, s[0:1]
	s_add_u32 s48, s2, 0x4000000
	v_or_b32_e32 v6, s18, v4
	v_mov_b64_e32 v[4:5], s[46:47]
	s_addc_u32 s49, s3, 0
	v_mad_u64_u32 v[6:7], s[2:3], v6, s53, v[4:5]
	s_mov_b32 s68, s50
	s_mov_b32 s69, s95
	v_mad_i32_i24 v7, s19, v156, v7
	s_lshl_b32 s94, s6, 1
	s_mov_b32 s70, s44
	s_mov_b32 s71, s95
	v_lshl_add_u64 v[8:9], v[6:7], 0, s[94:95]
	v_lshl_add_u64 v[10:11], v[6:7], 0, s[70:71]
	v_lshl_add_u64 v[6:7], v[6:7], 0, s[68:69]
	v_lshl_add_u64 v[8:9], v[8:9], 0, v[82:83]
	v_lshl_add_u64 v[6:7], v[6:7], 0, v[84:85]
	global_load_dword v119, v[8:9], off
	global_load_dword v118, v[8:9], off offset:512
	global_load_dwordx4 v[16:19], v[10:11], off
	global_load_dwordx4 v[12:15], v[10:11], off offset:16
	global_load_dwordx2 v[94:95], v[6:7], off offset:1024
	v_or_b32_e32 v6, 48, v99
	v_xor_b32_e32 v7, 0x7cf, v99
	v_cndmask_b32_e64 v6, v7, v6, s[0:1]
	v_or_b32_e32 v6, s18, v6
	v_mad_u64_u32 v[4:5], s[2:3], v6, s53, v[4:5]
	v_mad_i32_i24 v5, s19, v156, v5
	v_lshl_add_u64 v[6:7], v[4:5], 0, s[94:95]
	v_lshl_add_u64 v[6:7], v[6:7], 0, v[82:83]
	v_lshl_add_u64 v[22:23], v[4:5], 0, s[70:71]
	global_load_dword v117, v[6:7], off
	global_load_dword v116, v[6:7], off offset:512
	global_load_dwordx4 v[8:11], v[22:23], off
	v_lshl_add_u64 v[4:5], v[4:5], 0, s[68:69]
	v_lshl_add_u64 v[24:25], v[4:5], 0, v[84:85]
	global_load_dwordx4 v[4:7], v[22:23], off offset:16
	global_load_dwordx2 v[90:91], v[24:25], off offset:1024
	v_lshrrev_b32_e32 v21, 4, v2
	v_readlane_b32 s9, v248, 9
	s_waitcnt vmcnt(10)
	ds_write_b16 v104, v0 offset:18688
	ds_write_b16_d16_hi v104, v0 offset:18728
	ds_write_b16 v104, v1 offset:18768
	ds_write_b16_d16_hi v104, v1 offset:18808
	v_and_b32_e32 v1, 48, v2
	v_lshlrev_b32_e32 v2, 2, v21
	v_add_u32_e32 v108, v20, v1
	v_cmp_gt_u32_e64 s[6:7], v2, v99
	v_cmp_lt_u32_e64 s[8:9], v2, v99
	v_or_b32_e32 v20, 2, v2
	v_or_b32_e32 v2, 3, v2
	s_movk_i32 s2, 0x200
	v_cmp_gt_u32_e64 s[12:13], v2, v99
	v_ashrrev_i32_e32 v2, 2, v98
	v_cmp_gt_i32_e64 s[4:5], s2, v98
	v_and_or_b32 v2, v2, -16, v99
	s_movk_i32 s2, 0x210
	v_cmp_gt_u32_e64 s[10:11], v20, v99
	v_mul_lo_u32 v20, v2, 40
	v_mad_u32_u24 v2, v21, s2, v2
	v_lshlrev_b32_e32 v0, 3, v21
	v_lshl_add_u32 v110, v2, 1, 0
	v_lshlrev_b32_e32 v2, 5, v99
	v_add3_u32 v109, 0, v20, v0
	v_sub_u32_e32 v20, 0, v0
	v_add3_u32 v111, 0, v2, v0
	v_lshlrev_b32_e32 v0, 3, v98
	v_readlane_b32 s2, v247, 39
	s_waitcnt lgkmcnt(0)
	s_barrier
	v_mov_b32_e32 v36, 0
	v_add_u32_e32 v107, s2, v0
	v_readlane_b32 s2, v247, 40
	s_mov_b32 s35, 0
	v_add_u32_e32 v112, 0, v1
	v_add_u32_e32 v106, s2, v0
	v_readlane_b32 s2, v247, 41
	v_lshlrev_b32_e32 v105, 2, v98
	v_add_u32_e32 v115, v108, v20
	v_add_u32_e32 v113, s2, v0
	v_readlane_b32 s2, v247, 42
	v_mov_b32_e32 v37, v36
	v_mov_b32_e32 v38, v36
	v_add_u32_e32 v114, s2, v0
	v_mov_b32_e32 v39, v36
	v_mov_b32_e32 v40, v36
	v_mov_b32_e32 v41, v36
	v_mov_b32_e32 v42, v36
	v_mov_b32_e32 v43, v36
	v_mov_b32_e32 v44, v36
	v_mov_b32_e32 v45, v36
	v_mov_b32_e32 v46, v36
	v_mov_b32_e32 v47, v36
	v_mov_b32_e32 v48, v36
	v_mov_b32_e32 v49, v36
	v_mov_b32_e32 v50, v36
	v_mov_b32_e32 v51, v36
	v_readfirstlane_b32 vcc_lo, v147
	s_lshr_b32 vcc_lo, vcc_lo, 8
	s_cmp_eq_u32 vcc_lo, 0
	s_cbranch_scc1 .Lprio_skip2
	s_setprio 1
.Lprio_skip2:
	s_branch .LBB0_677
; template <int MODE>
; __device__ void scan_unit(int swave, const Params& p, int j, int b, int h, int dir, char* shm) {
;     ...
;   auto compute = [&](const char* buf, bf16_t* obuf) {
;     const bf16_t* qin = (const bf16_t*)buf; const bf16_t* ktil = (const bf16_t*)(buf + OFF_KT); const bf16_t* koutT = (const bf16_t*)(buf + OFF_KO);
;     const bf16_t* vT = (const bf16_t*)(buf + OFF_VT); const float* dec = (const float*)(buf + OFF_DEC);
;     bf16x8 Asc = {0, 0, 0, 0, 0, 0, 0, 0};
;     if (KS == 1 || wk == 0) {
;       f32x4 sc = {0.f, 0.f, 0.f, 0.f};
; #pragma unroll
;       for (int m = 0; m < DK / 32; ++m) {
;         const bf16x8 a = *(const bf16x8*)(ktil + r * QS + m * 32 + q4 * 8);
;         const bf16x8 bb = *(const bf16x8*)(qin + r * QS + m * 32 + q4 * 8);
;         sc = __builtin_amdgcn_mfma_f32_16x16x32_bf16(a, bb, sc, 0, 0, 0);
;       }
;       {
;         const unsigned p01 = pk2(q4 * 4 + 0 > r ? 0.f : sc[0], q4 * 4 + 1 > r ? 0.f : sc[1]);
;         const unsigned p23 = pk2(q4 * 4 + 2 > r ? 0.f : sc[2], q4 * 4 + 3 > r ? 0.f : sc[3]);
;         Asc[0] = (short)(p01 & 0xffff); Asc[1] = (short)(p01 >> 16); Asc[2] = (short)(p23 & 0xffff); Asc[3] = (short)(p23 >> 16);
;       }
;     }
;     bf16x8 Bv[NVT];
; #pragma unroll
;     for (int t = 0; t < NVT; ++t) {
;       const uint2 vv = *(const uint2*)(vT + ((vt0 + t) * 16 + r) * VS + q4 * 4);
;       Bv[t] = (bf16x8){(short)(vv.x & 0xffff), (short)(vv.x >> 16), (short)(vv.y & 0xffff), (short)(vv.y >> 16), 0, 0, 0, 0};
;     }
;     bf16x8 Aq[2];
; #pragma unroll
;     for (int m = 0; m < 2; ++m) {
;       const uint2 lo = *(const uint2*)(qin + r * QS + slab + (2 * m) * 16 + q4 * 4);
;       const uint2 hi = *(const uint2*)(qin + r * QS + slab + (2 * m + 1) * 16 + q4 * 4);
;       Aq[m] = (bf16x8){(short)(lo.x & 0xffff), (short)(lo.x >> 16), (short)(lo.y & 0xffff), (short)(lo.y >> 16),
;                        (short)(hi.x & 0xffff), (short)(hi.x >> 16), (short)(hi.y & 0xffff), (short)(hi.y >> 16)};
;     }
;     f32x4 o[NVT];
; #pragma unroll
;     for (int t = 0; t < NVT; ++t) {
;       o[t] = (f32x4){0.f, 0.f, 0.f, 0.f};
;       if (KS == 1 || wk == 0) o[t] = __builtin_amdgcn_mfma_f32_16x16x32_bf16(Asc, Bv[t], o[t], 0, 0, 0);
;     }
; #pragma unroll
;     for (int m = 0; m < 2; ++m)
; #pragma unroll
;       for (int t = 0; t < NVT; ++t) {
;         const f32x4 s0 = S[2 * m][t], s1 = S[2 * m + 1][t];
.LBB0_676:
	s_or_b64 exec, exec, s[2:3]
	ds_write_b16 v104, v92 offset:18688
	ds_write_b16_d16_hi v104, v92 offset:18728
	ds_write_b16 v104, v93 offset:18768
	ds_write_b16_d16_hi v104, v93 offset:18808
	ds_read_b128 v[20:23], v108 offset:26368
	ds_read_b128 v[24:27], v108 offset:24064
	ds_read_b128 v[28:31], v108 offset:26432
	ds_read_b128 v[32:35], v108 offset:24128
	v_add_u32_e32 v0, 0x5800, v115
	s_add_i32 s35, s35, 2
	s_waitcnt lgkmcnt(2)
	v_mfma_f32_16x16x32_bf16 v[20:23], v[20:23], v[24:27], 0
	ds_read_b64 v[24:25], v109 offset:30720
	ds_read2_b64 v[120:123], v0 offset0:192 offset1:196
	ds_read2_b64 v[126:129], v0 offset0:200 offset1:204
	v_mov_b32_e32 v26, v3
	v_mov_b32_e32 v27, v3
	s_waitcnt lgkmcnt(3)
	v_mfma_f32_16x16x32_bf16 v[20:23], v[28:31], v[32:35], v[20:23]
	s_waitcnt lgkmcnt(1)
	v_bfi_b32 v122, s30, v122, v122
	s_waitcnt lgkmcnt(0)
	v_bfi_b32 v128, s30, v128, v128
	v_cvt_pk_bf16_f32 v28, v40, v41
	v_cvt_pk_bf16_f32 v29, v42, v43
	v_cvt_pk_bf16_f32 v30, v44, v45
	s_nop 0
	v_cndmask_b32_e64 v0, v20, 0, s[6:7]
	v_cndmask_b32_e64 v1, 0, v21, s[8:9]
	v_cndmask_b32_e64 v2, v22, 0, s[10:11]
	v_cndmask_b32_e64 v20, v23, 0, s[12:13]
	v_cvt_pk_bf16_f32 v0, v0, v1
	v_cvt_pk_bf16_f32 v1, v2, v20
	v_mov_b32_e32 v2, v3
	v_cvt_pk_bf16_f32 v31, v46, v47
	s_and_b64 vcc, exec, s[72:73]
	v_mfma_f32_16x16x32_bf16 v[20:23], v[0:3], v[24:27], 0
	v_mfma_f32_16x16x32_bf16 v[20:23], v[120:123], v[28:31], v[20:23]
	v_cvt_pk_bf16_f32 v28, v48, v49
	v_cvt_pk_bf16_f32 v29, v50, v51
	v_cvt_pk_bf16_f32 v30, v36, v37
	v_cvt_pk_bf16_f32 v31, v38, v39
	s_nop 1
	v_mfma_f32_16x16x32_bf16 v[20:23], v[126:129], v[28:31], v[20:23]
	s_nop 7
	v_cvt_pk_bf16_f32 v0, v20, s0
	ds_write_b16 v110, v0 offset:56576
	v_cvt_pk_bf16_f32 v0, v21, s0
	ds_write_b16 v110, v0 offset:56840
	v_cvt_pk_bf16_f32 v0, v22, s0
	ds_write_b16 v110, v0 offset:57104
	v_cvt_pk_bf16_f32 v0, v23, s0
	ds_write_b16 v110, v0 offset:57368
	ds_read2st64_b64 v[20:23], v111 offset0:56 offset1:57
	ds_read2st64_b64 v[28:31], v111 offset0:58 offset1:59
	ds_read_b128 v[32:35], v112 offset:35840
	ds_read_b128 v[120:123], v112 offset:35904
	s_waitcnt lgkmcnt(3)
	v_mov_b32_e32 v0, v20
	v_mov_b32_e32 v1, v21
	s_waitcnt lgkmcnt(1)
	v_pk_mul_f32 v[34:35], v[42:43], v[34:35]
	v_pk_mul_f32 v[32:33], v[40:41], v[32:33]
	s_waitcnt lgkmcnt(0)
	v_pk_mul_f32 v[20:21], v[44:45], v[120:121]
	ds_read_b128 v[40:43], v112 offset:35968
	v_mfma_f32_16x16x32_bf16 v[32:35], v[0:3], v[24:27], v[32:35]
	v_mov_b32_e32 v0, v22
	v_mov_b32_e32 v1, v23
	v_pk_mul_f32 v[22:23], v[46:47], v[122:123]
	ds_read_b128 v[44:47], v112 offset:36032
	s_waitcnt lgkmcnt(1)
	v_pk_mul_f32 v[42:43], v[50:51], v[42:43]
	v_mfma_f32_16x16x32_bf16 v[20:23], v[0:3], v[24:27], v[20:23]
	v_mov_b32_e32 v0, v28
	v_mov_b32_e32 v1, v29
	v_pk_mul_f32 v[40:41], v[48:49], v[40:41]
	v_mov_b32_e32 v122, v3
	v_mov_b32_e32 v123, v3
	v_mfma_f32_16x16x32_bf16 v[40:43], v[0:3], v[24:27], v[40:43]
	v_mov_b32_e32 v0, v30
	v_mov_b32_e32 v1, v31
	ds_read_b128 v[28:31], v108 offset:38400
	s_waitcnt lgkmcnt(1)
	v_pk_mul_f32 v[38:39], v[38:39], v[46:47]
	v_pk_mul_f32 v[36:37], v[36:37], v[44:45]
	s_nop 1
	v_mfma_f32_16x16x32_bf16 v[24:27], v[0:3], v[24:27], v[36:39]
	s_nop 2
	ds_read_b128 v[36:39], v108 offset:38464
	ds_read_b128 v[44:47], v108 offset:36096
	ds_read_b128 v[48:51], v108 offset:36160
	s_waitcnt lgkmcnt(1)
	v_mfma_f32_16x16x32_bf16 v[28:31], v[28:31], v[44:47], 0
	s_waitcnt lgkmcnt(0)
	v_mfma_f32_16x16x32_bf16 v[28:31], v[36:39], v[48:51], v[28:31]
	v_add_u32_e32 v36, 0x8800, v115
	v_cvt_pk_bf16_f32 v48, v32, v33
	v_cvt_pk_bf16_f32 v49, v34, v35
	v_cvt_pk_bf16_f32 v50, v20, v21
	v_cvt_pk_bf16_f32 v51, v22, v23
	s_nop 2
	v_cndmask_b32_e64 v0, v28, 0, s[6:7]
	v_cndmask_b32_e64 v1, 0, v29, s[8:9]
	v_cvt_pk_bf16_f32 v0, v0, v1
	v_cndmask_b32_e64 v1, v30, 0, s[10:11]
	v_cndmask_b32_e64 v2, v31, 0, s[12:13]
	ds_read2_b64 v[28:31], v36 offset0:160 offset1:164
	ds_read2_b64 v[36:39], v36 offset0:168 offset1:172
	v_cvt_pk_bf16_f32 v1, v1, v2
	ds_read_b64 v[120:121], v109 offset:42752
	v_mov_b32_e32 v2, v3
	s_waitcnt lgkmcnt(2)
	v_bfi_b32 v30, s30, v30, v30
	s_waitcnt lgkmcnt(1)
	v_bfi_b32 v38, s30, v38, v38
	s_waitcnt lgkmcnt(0)
	v_mfma_f32_16x16x32_bf16 v[44:47], v[0:3], v[120:123], 0
	v_mfma_f32_16x16x32_bf16 v[28:31], v[28:31], v[48:51], v[44:47]
	s_nop 6
	v_cvt_pk_bf16_f32 v44, v40, v41
	v_cvt_pk_bf16_f32 v45, v42, v43
	v_cvt_pk_bf16_f32 v46, v24, v25
	v_cvt_pk_bf16_f32 v47, v26, v27
	s_nop 1
	v_mfma_f32_16x16x32_bf16 v[28:31], v[36:39], v[44:47], v[28:31]
	s_nop 7
	v_cvt_pk_bf16_f32 v0, v28, s0
	ds_write_b16 v110, v0 offset:60800
	v_cvt_pk_bf16_f32 v0, v29, s0
	ds_write_b16 v110, v0 offset:61064
	v_cvt_pk_bf16_f32 v0, v30, s0
	ds_write_b16 v110, v0 offset:61328
	v_cvt_pk_bf16_f32 v0, v31, s0
	ds_write_b16 v110, v0 offset:61592
	ds_read2st64_b64 v[28:31], v124 offset0:79 offset1:80
	ds_read2st64_b64 v[36:39], v124 offset0:81 offset1:82
	ds_read_b128 v[44:47], v112 offset:47872
	ds_read_b128 v[124:127], v112 offset:47936
	s_waitcnt lgkmcnt(3)
	v_mov_b32_e32 v0, v28
	v_mov_b32_e32 v1, v29
	s_waitcnt lgkmcnt(1)
	v_pk_mul_f32 v[34:35], v[34:35], v[46:47]
	v_pk_mul_f32 v[32:33], v[32:33], v[44:45]
	s_waitcnt lgkmcnt(0)
	v_pk_mul_f32 v[22:23], v[22:23], v[126:127]
	v_pk_mul_f32 v[20:21], v[20:21], v[124:125]
	v_mfma_f32_16x16x32_bf16 v[48:51], v[0:3], v[120:123], v[32:35]
	v_mov_b32_e32 v0, v30
	v_mov_b32_e32 v1, v31
	ds_read_b128 v[28:31], v112 offset:48064
	s_nop 0
	v_mfma_f32_16x16x32_bf16 v[44:47], v[0:3], v[120:123], v[20:23]
	v_mov_b32_e32 v0, v36
	s_nop 1
	ds_read_b128 v[20:23], v112 offset:48000
	v_mov_b32_e32 v1, v37
	s_waitcnt lgkmcnt(0)
	s_barrier
	s_waitcnt lgkmcnt(0)
	v_pk_mul_f32 v[22:23], v[42:43], v[22:23]
	v_pk_mul_f32 v[20:21], v[40:41], v[20:21]
	s_nop 1
	v_mfma_f32_16x16x32_bf16 v[40:43], v[0:3], v[120:123], v[20:23]
	v_mov_b32_e32 v0, v38
	v_mov_b32_e32 v1, v39
	s_nop 0
	v_pk_mul_f32 v[22:23], v[26:27], v[30:31]
	v_pk_mul_f32 v[20:21], v[24:25], v[28:29]
	s_nop 1
	v_mfma_f32_16x16x32_bf16 v[36:39], v[0:3], v[120:123], v[20:23]
	s_cbranch_vccnz .LBB0_695

; __device__ __forceinline__ unsigned pk2(float lo, float hi) { f32x2_t v = {lo, hi}; bf16x2_t b = __builtin_convertvector(v, bf16x2_t); return __builtin_bit_cast(unsigned, b); }
; __device__ __forceinline__ float lo_bf(unsigned u) { return __uint_as_float(u << 16); }
; __device__ __forceinline__ float hi_bf(unsigned u) { return __uint_as_float(u & 0xffff0000u); }
; template <int MODE>
; __device__ void scan_unit(int swave, const Params& p, int j, int b, int h, int dir, char* shm) {
;     ...
;   auto ostore = [&](int c, const bf16_t* obuf) {
;     for (int idx = tid; idx < 16 * DV / 4; idx += 512) {
;       const int i = idx / (DV / 4), cc = (idx % (DV / 4)) * 4;
;       uint2 o = *(const uint2*)(obuf + i * OS + cc);
;       if (KS == 2) {
;         const uint2 o2 = *(const uint2*)(obuf + (16 + i) * OS + cc);
;         o.x = pk2(lo_bf(o.x) + lo_bf(o2.x), hi_bf(o.x) + hi_bf(o2.x)); o.y = pk2(lo_bf(o.y) + lo_bf(o2.y), hi_bf(o.y) + hi_bf(o2.y));
;       }
;       *(uint2*)(O + (rowbase + tokof(c, i)) * OLD + cc) = o;
;     }
.LBB0_695:
	s_setprio 0
	s_and_saveexec_b64 s[2:3], s[4:5]
	s_cbranch_execz .LBB0_633
	s_mov_b64 s[4:5], 0
	v_mov_b32_e32 v0, v105
	v_mov_b32_e32 v1, v98
	s_waitcnt vmcnt(0)
